# code placement: the four hand-written SSD chunk loops aligned to 64 bytes
# speedup vs baseline: 1.0017x; 1.0006x over previous
; __device__ __forceinline__ unsigned cvt_pk_bf16(float lo, float hi) { unsigned r; asm volatile("v_cvt_pk_bf16_f32 %0, %1, %2" : "=v"(r) : "v"(lo), "v"(hi)); return r; }
; __device__ __forceinline__ void phase_ssd(const Params& P, int seg, unsigned char* smem) {
;     ...
;             { const float e2 = __expf(R.alast - R.acl);
; #pragma unroll
;               for (int i = 0; i < 2; ++i) { const int q = tid + 512 * i, l = q >> 4, c8 = q & 15; *(v4u*)(sb + T_CS + l * 272 + c8 * 16) = R.Cr[i]; *(v4u*)(sb + T_BS + l * 272 + c8 * 16) = R.Br[i]; }
;               const int l = tid >> 3, p4 = (tid & 7) * 4;
;               const float x0 = bflo(R.Xr.x) * R.dtl, x1 = bfhi(R.Xr.x) * R.dtl, x2 = bflo(R.Xr.y) * R.dtl, x3 = bfhi(R.Xr.y) * R.dtl;
;               v2u d; d.x = cvt_pk_bf16(x0, x1); d.y = cvt_pk_bf16(x2, x3); *(v2u*)(sb + T_XD + l * 80 + p4 * 2) = d;
;               v2u e; e.x = cvt_pk_bf16(x0 * e2, x1 * e2); e.y = cvt_pk_bf16(x2 * e2, x3 * e2); *(v2u*)(sb + T_XE + l * 80 + p4 * 2) = e;
;               *(v2u*)(sb + T_XS + l * 64 + p4 * 2) = R.Xr; *(v2u*)(sb + T_ZS + l * 64 + p4 * 2) = R.Zr;
;               if (w == 0) acP[lane] = R.aclane; }
;             BAR_LDS();
;             if (ci + 2 < nchunks) load_chunk(ci + 2, R);
;             bf16x8 cf[4];
; #pragma unroll
;             for (int k = 0; k < 4; ++k) cf[k] = *(const bf16x8*)(sb + T_CS + (lt * 16 + fr) * 272 + (k * 32 + fq * 8) * 2);
;             f32x4 yo = {0.f, 0.f, 0.f, 0.f};
; #pragma unroll
;             for (int k = 0; k < 4; ++k) { const bf16x8 bb = *(const bf16x8*)((const unsigned char*)StR + (pt * 16 + fr) * 272 + (k * 32 + fq * 8) * 2); yo = mfma16(cf[k], bb, yo); }
; { const f32x4 a4 = *(const f32x4*)(acP + lt * 16 + fq * 4);
; #pragma unroll
;               for (int j = 0; j < 4; ++j) yo[j] *= __expf(a4[j]); }
;             const float acl_fr = acP[lt * 16 + fr]; const int lrow = lt * 16 + fr;
; #pragma unroll
;             for (int t = 0; t < 2; ++t) {
;                 if (2 * t <= lt) {
;                     v2u xb0, xb1;
;                     { const unsigned a0 = lds0 + par * T_BUF + T_XD + (32 * t + 4 * fq + tq) * 80 + (pt * 16 + 4 * tp) * 2, a1 = a0 + 16 * 80; TR_ISSUE(xb0, a0); TR_ISSUE(xb1, a1); }
;                     float m[8];
;                     { f32x4 s0 = {0.f, 0.f, 0.f, 0.f}, s1 = {0.f, 0.f, 0.f, 0.f};
; #pragma unroll
.Lssd_noimg:
	ds_write_b128 v212, v[140:143]
	ds_write_b128 v212, v[144:147] offset:8192
	ds_write_b128 v212, v[132:135] offset:16384
	ds_write_b128 v212, v[136:139] offset:24576
	v_sub_f32_e32 v200, v117, v116
	v_mul_f32_e32 v200, 0x3fb8aa3b, v200
	v_exp_f32_e32 v200, v200
	v_lshlrev_b32_e32 v196, 16, v4
	v_and_b32_e32 v197, 0xffff0000, v4
	v_lshlrev_b32_e32 v198, 16, v5
	v_and_b32_e32 v199, 0xffff0000, v5
	v_mul_f32_e32 v196, v196, v6
	v_mul_f32_e32 v197, v197, v6
	v_mul_f32_e32 v198, v198, v6
	v_mul_f32_e32 v199, v199, v6
	v_cvt_pk_bf16_f32 v202, v196, v197
	v_cvt_pk_bf16_f32 v203, v198, v199
	ds_write_b64 v214, v[202:203] offset:32768
	v_mul_f32_e32 v196, v196, v200
	v_mul_f32_e32 v197, v197, v200
	v_mul_f32_e32 v198, v198, v200
	v_mul_f32_e32 v199, v199, v200
	v_cvt_pk_bf16_f32 v192, v196, v197
	v_cvt_pk_bf16_f32 v193, v198, v199
	ds_write_b64 v214, v[192:193] offset:37888
	ds_write_b64 v216, v[4:5] offset:43008
	ds_write_b64 v216, v[36:37] offset:47616
	v_mul_f32_e32 v201, 0x3fb8aa3b, v116
	ds_write_b32 v218, v201
	v_mul_f32_e32 v174, 0x3fb8aa3b, v117
	v_exp_f32_e32 v174, v174
	s_waitcnt lgkmcnt(0)
	s_barrier
	s_cmp_eq_u32 s55, 1
	s_cbranch_scc1 .Lssd_loop1
	s_cmp_eq_u32 s55, 2
	s_cbranch_scc1 .Lssd_loop2
	s_cmp_eq_u32 s55, 3
	s_cbranch_scc1 .Lssd_loop3
	.p2align	6
.Lssd_loop0:
	ds_read_b128 v[28:31], v219
	ds_read_b128 v[32:35], v220
	ds_read_b128 v[40:43], v221
	ds_read_b128 v[44:47], v222
	ds_read_b128 v[48:51], v227
	ds_read_b128 v[52:55], v228
	ds_read_b128 v[56:59], v229
	ds_read_b128 v[60:63], v230
	ds_read_b32 v194, v231
	ds_read_b64_tr_b16 v[96:97], v244 offset:16384
	ds_read_b64_tr_b16 v[98:99], v244 offset:20480
	ds_read_b64_tr_b16 v[100:101], v244 offset:24576
	ds_read_b64_tr_b16 v[102:103], v244 offset:28672
	ds_read_b64_tr_b16 v[104:105], v245 offset:16384
	ds_read_b64_tr_b16 v[106:107], v245 offset:20480
	s_waitcnt lgkmcnt(11)
	ds_read_b64_tr_b16 v[108:109], v245 offset:24576
	ds_read_b64_tr_b16 v[110:111], v245 offset:28672
	ds_read_b64_tr_b16 v[112:113], v237 offset:37888
	ds_read_b64_tr_b16 v[114:115], v237 offset:39168
	s_waitcnt lgkmcnt(11)
	ds_read_b64_tr_b16 v[124:125], v237 offset:37920
	ds_read_b64_tr_b16 v[126:127], v237 offset:39200
	ds_read_b64_tr_b16 v[120:121], v237 offset:40448
	ds_read_b64_tr_b16 v[122:123], v237 offset:41728
	global_load_dwordx4 v[140:143], v204, s[40:41] offset:2048
	s_waitcnt lgkmcnt(11)
	ds_read_b64_tr_b16 v[128:129], v237 offset:40480
	ds_read_b64_tr_b16 v[130:131], v237 offset:41760
	ds_read_b128 v[64:67], v219 offset:16384
	ds_read_b128 v[68:71], v220 offset:16384
	s_waitcnt lgkmcnt(11)
	ds_read_b128 v[72:75], v221 offset:16384
	global_load_dwordx4 v[144:147], v205, s[40:41] offset:2048
	ds_read_b128 v[76:79], v222 offset:16384
	v_mfma_f32_16x16x32_bf16 v[24:27], v[48:51], v[28:31], 0
	v_mfma_f32_16x16x32_bf16 v[24:27], v[52:55], v[32:35], v[24:27]
	v_mfma_f32_16x16x32_bf16 v[24:27], v[56:59], v[40:43], v[24:27]
	v_mfma_f32_16x16x32_bf16 v[24:27], v[60:63], v[44:47], v[24:27]
	global_load_dwordx4 v[132:135], v204, s[40:41]
	ds_read_b64_tr_b16 v[56:57], v233 offset:32768
	ds_read_b64_tr_b16 v[58:59], v233 offset:34048
	v_mul_f32_e32 v8, v8, v174
	v_mul_f32_e32 v9, v9, v174
	v_mul_f32_e32 v10, v10, v174
	v_mul_f32_e32 v11, v11, v174
	global_load_dwordx4 v[136:139], v205, s[40:41]
	v_mul_f32_e32 v12, v12, v174
	v_mul_f32_e32 v13, v13, v174
	v_mul_f32_e32 v14, v14, v174
	v_mul_f32_e32 v15, v15, v174
	v_mul_f32_e32 v16, v16, v174
	global_load_dwordx2 v[4:5], v206, s[40:41]
	v_mul_f32_e32 v17, v17, v174
	v_mul_f32_e32 v18, v18, v174
	v_mul_f32_e32 v19, v19, v174
	v_mul_f32_e32 v20, v20, v174
	v_mul_f32_e32 v21, v21, v174
	global_load_dwordx2 v[36:37], v207, s[42:43] nt
	v_mul_f32_e32 v22, v22, v174
	v_mul_f32_e32 v23, v23, v174
	s_waitcnt lgkmcnt(12)
	v_mfma_f32_16x16x32_bf16 v[8:11], v[96:99], v[112:115], v[8:11]
	s_waitcnt lgkmcnt(10)
	v_mfma_f32_16x16x32_bf16 v[12:15], v[96:99], v[124:127], v[12:15]
	v_mfma_f32_16x16x32_bf16 v[16:19], v[104:107], v[112:115], v[16:19]
	v_mfma_f32_16x16x32_bf16 v[20:23], v[104:107], v[124:127], v[20:23]
	global_load_dword v6, v208, s[44:45]
	s_waitcnt lgkmcnt(8)
	v_mfma_f32_16x16x32_bf16 v[8:11], v[100:103], v[120:123], v[8:11]
	s_waitcnt lgkmcnt(6)
	v_mfma_f32_16x16x32_bf16 v[12:15], v[100:103], v[128:131], v[12:15]
	v_mfma_f32_16x16x32_bf16 v[16:19], v[108:111], v[120:123], v[16:19]
	v_mfma_f32_16x16x32_bf16 v[20:23], v[108:111], v[128:131], v[20:23]
	ds_read_b128 v[96:99], v232
	global_load_dword v116, v208, s[46:47]
	ds_read_b64 v[124:125], v235 offset:43008
	ds_read_b64 v[126:127], v235 offset:47616
	s_waitcnt lgkmcnt(8)
	v_mfma_f32_16x16x32_bf16 v[48:51], v[64:67], v[28:31], 0
	s_waitcnt lgkmcnt(7)
	v_mfma_f32_16x16x32_bf16 v[48:51], v[68:71], v[32:35], v[48:51]
	s_waitcnt lgkmcnt(6)
	v_mfma_f32_16x16x32_bf16 v[48:51], v[72:75], v[40:43], v[48:51]
	global_load_dword v117, v209, s[46:47]
	s_waitcnt lgkmcnt(5)
	v_mfma_f32_16x16x32_bf16 v[48:51], v[76:79], v[44:47], v[48:51]
	v_exp_f32_e32 v195, v194
	s_nop 0
	v_mul_f32_e32 v24, v24, v195
	v_mul_f32_e32 v25, v25, v195
	v_mul_f32_e32 v26, v26, v195
	v_mul_f32_e32 v27, v27, v195
	s_add_u32 s66, s54, 3
	s_cmp_lt_u32 s66, s39
	s_cselect_b32 s74, 0xc0000, 0
	s_cselect_b32 s75, 0x280000, 0
	s_cselect_b32 s76, 0x4000, 0
	s_add_u32 s40, s40, s74
	s_addc_u32 s41, s41, 0
	s_add_u32 s42, s42, s75
	s_addc_u32 s43, s43, 0
	s_add_u32 s44, s44, s76
	s_addc_u32 s45, s45, 0
	s_add_u32 s46, s46, s76
	s_addc_u32 s47, s47, 0
	v_cvt_pk_bf16_f32 v184, v8, v9
	s_waitcnt vmcnt(10)
; __device__ __forceinline__ void phase_ssd(const Params& P, int seg, unsigned char* smem) {
;     ...
;                           const float e0 = s0[j] * __expf(fminf(acl_fr - a0[j], 0.f)), e1 = s1[j] * __expf(fminf(acl_fr - a1[j], 0.f));
;                           m[j] = (si0 <= lrow) ? e0 : 0.f; m[4 + j] = (si1 <= lrow) ? e1 : 0.f; } }
;                     v4u mp; mp.x = cvt_pk_bf16(m[0], m[1]); mp.y = cvt_pk_bf16(m[2], m[3]); mp.z = cvt_pk_bf16(m[4], m[5]); mp.w = cvt_pk_bf16(m[6], m[7]);
;                     asm volatile("s_waitcnt lgkmcnt(0)" : "+v"(xb0), "+v"(xb1) :: "memory");
;                     yo = mfma16(__builtin_bit_cast(bf16x8, mp), mk8(xb0, xb1), yo);
;                 }
;             }
; #pragma unroll
;             for (int j = 0; j < 4; ++j) { const int l = lt * 16 + fq * 4 + j, p = pt * 16 + fr; const float xv = bf2f(*(const bf16*)(sb + T_XS + l * 64 + p * 2)), zv = bf2f(*(const bf16*)(sb + T_ZS + l * 64 + p * 2));
;                 ypre[(size_t)(row0 + l) * DINNER + h * 64 + ph * 32 + p] = f2bfh((yo[j] + Dh * xv) * siluf_(zv)); }
;             { v2u xa[2][2][2], bb[2][2];
; #pragma unroll
;               for (int kk = 0; kk < 2; ++kk) {
; #pragma unroll
;                   for (int hh = 0; hh < 2; ++hh) { const int r = kk * 32 + 8 * fq + 4 * hh + tq;
;                       TR_ISSUE(bb[kk][hh], lds0 + par * T_BUF + T_BS + r * 272 + (w * 16 + 4 * tp) * 2);
; #pragma unroll
;                       for (int p2 = 0; p2 < 2; ++p2) TR_ISSUE(xa[p2][kk][hh], lds0 + par * T_BUF + T_XE + r * 80 + (p2 * 16 + 4 * tp) * 2); } }
;               asm volatile("s_waitcnt lgkmcnt(0)" : "+v"(xa[0][0][0]), "+v"(xa[0][0][1]), "+v"(xa[0][1][0]), "+v"(xa[0][1][1]), "+v"(xa[1][0][0]), "+v"(xa[1][0][1]), "+v"(xa[1][1][0]), "+v"(xa[1][1][1]),
;                            "+v"(bb[0][0]), "+v"(bb[0][1]), "+v"(bb[1][0]), "+v"(bb[1][1]) :: "memory");
; #pragma unroll
;               for (int p2 = 0; p2 < 2; ++p2) { st[p2] *= dec;
; #pragma unroll
;                   for (int kk = 0; kk < 2; ++kk) st[p2] = mfma16(mk8(xa[p2][kk][0], xa[p2][kk][1]), mk8(bb[kk][0], bb[kk][1]), st[p2]); } }
; #pragma unroll
;             for (int p2 = 0; p2 < 2; ++p2)
; #pragma unroll
;                 for (int j = 0; j < 4; ++j) StW[(p2 * 16 + fq * 4 + j) * 136 + w * 16 + fr] = (bf16)f2bf(st[p2][j]);
;         };
	v_cvt_pk_bf16_f32 v185, v10, v11
	v_cvt_pk_bf16_f32 v186, v12, v13
	ds_write_b128 v213, v[156:159]
	v_cvt_pk_bf16_f32 v187, v14, v15
	v_cvt_pk_bf16_f32 v188, v16, v17
	ds_write_b128 v213, v[160:163] offset:8192
	v_cvt_pk_bf16_f32 v189, v18, v19
	v_cvt_pk_bf16_f32 v190, v20, v21
	ds_write_b128 v213, v[148:151] offset:16384
	v_cvt_pk_bf16_f32 v191, v22, v23
	ds_write_b64 v248, v[184:185] offset:8192
	ds_write_b128 v213, v[152:155] offset:24576
	ds_write_b64 v248, v[186:187] offset:12288
	v_sub_f32_e32 v200, v169, v168
	ds_write_b64 v249, v[188:189] offset:8192
	ds_write_b64 v249, v[190:191] offset:12288
	v_mul_f32_e32 v200, 0x3fb8aa3b, v200
	s_waitcnt lgkmcnt(8)
	v_lshlrev_b32_e32 v112, 16, v126
	v_and_b32_e32 v113, 0xffff0000, v126
	v_exp_f32_e32 v200, v200
	v_lshlrev_b32_e32 v114, 16, v127
	v_and_b32_e32 v115, 0xffff0000, v127
	v_lshlrev_b32_e32 v196, 16, v164
	v_mul_f32_e32 v120, 0xbfb8aa3b, v112
	v_and_b32_e32 v197, 0xffff0000, v164
	v_mul_f32_e32 v121, 0xbfb8aa3b, v113
	v_mul_f32_e32 v122, 0xbfb8aa3b, v114
	v_lshlrev_b32_e32 v198, 16, v165
	v_mul_f32_e32 v123, 0xbfb8aa3b, v115
	v_exp_f32_e32 v120, v120
	v_and_b32_e32 v199, 0xffff0000, v165
	v_exp_f32_e32 v121, v121
	v_exp_f32_e32 v122, v122
	v_mul_f32_e32 v196, v196, v118
	v_exp_f32_e32 v123, v123
	v_add_f32_e32 v120, 1.0, v120
	v_mul_f32_e32 v197, v197, v118
	v_add_f32_e32 v121, 1.0, v121
	v_mul_f32_e32 v198, v198, v118
	v_add_f32_e32 v122, 1.0, v122
	v_add_f32_e32 v123, 1.0, v123
	v_mul_f32_e32 v199, v199, v118
	v_rcp_f32_e32 v120, v120
	v_rcp_f32_e32 v121, v121
	v_cvt_pk_bf16_f32 v202, v196, v197
	v_rcp_f32_e32 v122, v122
	v_rcp_f32_e32 v123, v123
	v_cvt_pk_bf16_f32 v203, v198, v199
	v_mul_f32_e32 v112, v120, v112
	v_mul_f32_e32 v113, v121, v113
	ds_write_b64 v215, v[202:203] offset:32768
	v_mul_f32_e32 v114, v122, v114
	v_mul_f32_e32 v196, v196, v200
	v_mul_f32_e32 v115, v123, v115
	v_lshlrev_b32_e32 v120, 16, v124
	v_mul_f32_e32 v197, v197, v200
	v_and_b32_e32 v121, 0xffff0000, v124
	v_lshlrev_b32_e32 v122, 16, v125
	v_mul_f32_e32 v198, v198, v200
	v_and_b32_e32 v123, 0xffff0000, v125
	v_sub_f32_e32 v184, v194, v96
	v_mul_f32_e32 v199, v199, v200
	v_sub_f32_e32 v185, v194, v97
	v_cvt_pk_bf16_f32 v192, v196, v197
	v_sub_f32_e32 v186, v194, v98
	v_sub_f32_e32 v187, v194, v99
	v_cvt_pk_bf16_f32 v193, v198, v199
	v_exp_f32_e32 v184, v184
	v_exp_f32_e32 v185, v185
	ds_write_b64 v215, v[192:193] offset:37888
	v_exp_f32_e32 v186, v186
	v_exp_f32_e32 v187, v187
	ds_write_b64 v217, v[164:165] offset:43008
	v_mul_f32_e32 v184, v48, v184
	v_mul_f32_e32 v185, v49, v185
	ds_write_b64 v217, v[166:167] offset:47616
	v_mul_f32_e32 v186, v50, v186
	v_mul_f32_e32 v201, 0x3fb8aa3b, v168
	v_mul_f32_e32 v187, v51, v187
	v_cndmask_b32_e64 v184, 0, v184, s[14:15]
	ds_write_b32 v218, v201 offset:256
	v_cndmask_b32_e64 v185, 0, v185, s[16:17]
	v_cndmask_b32_e64 v186, 0, v186, s[22:23]
	v_mul_f32_e32 v174, 0x3fb8aa3b, v169
	v_cndmask_b32_e64 v187, 0, v187, s[34:35]
	v_cvt_pk_bf16_f32 v128, v184, v185
	v_exp_f32_e32 v174, v174
	v_cvt_pk_bf16_f32 v129, v186, v187
	v_mov_b32_e32 v130, 0
	v_mov_b32_e32 v131, 0
	s_nop 1
	v_mfma_f32_16x16x32_bf16 v[24:27], v[56:59], v[128:131], v[24:27]
	s_mul_i32 s65, s56, 0x2000
	s_add_u32 s65, s65, 0x304f1000
	s_add_u32 s48, s0, s65
	s_addc_u32 s49, s1, 0
	s_nop 3
	v_fma_f32 v184, s61, v120, v24
	v_fma_f32 v185, s61, v121, v25
	v_fma_f32 v186, s61, v122, v26
	v_fma_f32 v187, s61, v123, v27
	v_mul_f32_e32 v184, v184, v112
	v_mul_f32_e32 v185, v185, v113
	v_mul_f32_e32 v186, v186, v114
	v_mul_f32_e32 v187, v187, v115
	v_cvt_pk_bf16_f32 v170, v184, v185
	v_cvt_pk_bf16_f32 v171, v186, v187
	global_store_dwordx2 v210, v[170:171], s[48:49]
	s_add_u32 s65, s54, 1
	s_sub_u32 s65, s65, s60
	s_lshl_b32 s65, s65, 6
	s_add_u32 s56, s65, s20
	s_waitcnt lgkmcnt(0)
	s_barrier
	s_add_u32 s54, s54, 1
	s_cmp_ge_u32 s54, s39
	s_cbranch_scc1 .Lssd_done
	ds_read_b128 v[28:31], v223
	ds_read_b128 v[32:35], v224
	ds_read_b128 v[40:43], v225
	ds_read_b128 v[44:47], v226
	ds_read_b128 v[48:51], v227 offset:8192
	ds_read_b128 v[52:55], v228 offset:8192
	ds_read_b128 v[56:59], v229 offset:8192
	ds_read_b128 v[60:63], v230 offset:8192
	ds_read_b32 v194, v231 offset:256
	ds_read_b64_tr_b16 v[96:97], v246 offset:16384
	ds_read_b64_tr_b16 v[98:99], v246 offset:20480
	ds_read_b64_tr_b16 v[100:101], v246 offset:24576
	ds_read_b64_tr_b16 v[102:103], v246 offset:28672
	ds_read_b64_tr_b16 v[104:105], v247 offset:16384
	ds_read_b64_tr_b16 v[106:107], v247 offset:20480
	s_waitcnt lgkmcnt(11)
	ds_read_b64_tr_b16 v[108:109], v247 offset:24576
	ds_read_b64_tr_b16 v[110:111], v247 offset:28672
	ds_read_b64_tr_b16 v[112:113], v243 offset:37888
	ds_read_b64_tr_b16 v[114:115], v243 offset:39168
	s_waitcnt lgkmcnt(11)
	ds_read_b64_tr_b16 v[124:125], v243 offset:37920
	ds_read_b64_tr_b16 v[126:127], v243 offset:39200
	ds_read_b64_tr_b16 v[120:121], v243 offset:40448
	ds_read_b64_tr_b16 v[122:123], v243 offset:41728
	global_load_dwordx4 v[156:159], v204, s[40:41] offset:2048
	s_waitcnt lgkmcnt(11)
	ds_read_b64_tr_b16 v[128:129], v243 offset:40480
	ds_read_b64_tr_b16 v[130:131], v243 offset:41760
	ds_read_b128 v[64:67], v223 offset:16384
	ds_read_b128 v[68:71], v224 offset:16384
	s_waitcnt lgkmcnt(11)
; __device__ __forceinline__ void phase_ssd(const Params& P, int seg, unsigned char* smem) {
;     ...
;             if (ci + 2 < nchunks) load_chunk(ci + 2, R);
;             bf16x8 cf[4];
; #pragma unroll
;             for (int k = 0; k < 4; ++k) cf[k] = *(const bf16x8*)(sb + T_CS + (lt * 16 + fr) * 272 + (k * 32 + fq * 8) * 2);
;             f32x4 yo = {0.f, 0.f, 0.f, 0.f};
; #pragma unroll
;             for (int k = 0; k < 4; ++k) { const bf16x8 bb = *(const bf16x8*)((const unsigned char*)StR + (pt * 16 + fr) * 272 + (k * 32 + fq * 8) * 2); yo = mfma16(cf[k], bb, yo); }
; { const f32x4 a4 = *(const f32x4*)(acP + lt * 16 + fq * 4);
; #pragma unroll
;               for (int j = 0; j < 4; ++j) yo[j] *= __expf(a4[j]); }
;             const float acl_fr = acP[lt * 16 + fr]; const int lrow = lt * 16 + fr;
; #pragma unroll
;             for (int t = 0; t < 2; ++t) {
;                 if (2 * t <= lt) {
;                     v2u xb0, xb1;
;                     { const unsigned a0 = lds0 + par * T_BUF + T_XD + (32 * t + 4 * fq + tq) * 80 + (pt * 16 + 4 * tp) * 2, a1 = a0 + 16 * 80; TR_ISSUE(xb0, a0); TR_ISSUE(xb1, a1); }
;                     float m[8];
;                     { f32x4 s0 = {0.f, 0.f, 0.f, 0.f}, s1 = {0.f, 0.f, 0.f, 0.f};
; #pragma unroll
;                       for (int k = 0; k < 4; ++k) { const bf16x8 bf0 = *(const bf16x8*)(sb + T_BS + ((2 * t) * 16 + fr) * 272 + (k * 32 + fq * 8) * 2), bf1 = *(const bf16x8*)(sb + T_BS + ((2 * t + 1) * 16 + fr) * 272 + (k * 32 + fq * 8) * 2);
;                           s0 = mfma16(bf0, cf[k], s0); s1 = mfma16(bf1, cf[k], s1); }
;                       const f32x4 a0 = *(const f32x4*)(acP + (2 * t) * 16 + fq * 4), a1 = *(const f32x4*)(acP + (2 * t + 1) * 16 + fq * 4);
; #pragma unroll
;                       for (int j = 0; j < 4; ++j) { const int si0 = (2 * t) * 16 + fq * 4 + j, si1 = si0 + 16;
;                           const float e0 = s0[j] * __expf(fminf(acl_fr - a0[j], 0.f)), e1 = s1[j] * __expf(fminf(acl_fr - a1[j], 0.f));
;                           m[j] = (si0 <= lrow) ? e0 : 0.f; m[4 + j] = (si1 <= lrow) ? e1 : 0.f; } }
;                     v4u mp; mp.x = cvt_pk_bf16(m[0], m[1]); mp.y = cvt_pk_bf16(m[2], m[3]); mp.z = cvt_pk_bf16(m[4], m[5]); mp.w = cvt_pk_bf16(m[6], m[7]);
;                     asm volatile("s_waitcnt lgkmcnt(0)" : "+v"(xb0), "+v"(xb1) :: "memory");
	ds_read_b128 v[72:75], v225 offset:16384
	global_load_dwordx4 v[160:163], v205, s[40:41] offset:2048
	ds_read_b128 v[76:79], v226 offset:16384
	v_mfma_f32_16x16x32_bf16 v[24:27], v[48:51], v[28:31], 0
	v_mfma_f32_16x16x32_bf16 v[24:27], v[52:55], v[32:35], v[24:27]
	v_mfma_f32_16x16x32_bf16 v[24:27], v[56:59], v[40:43], v[24:27]
	v_mfma_f32_16x16x32_bf16 v[24:27], v[60:63], v[44:47], v[24:27]
	global_load_dwordx4 v[148:151], v204, s[40:41]
	ds_read_b64_tr_b16 v[56:57], v234 offset:32768
	ds_read_b64_tr_b16 v[58:59], v234 offset:34048
	v_mul_f32_e32 v8, v8, v174
	v_mul_f32_e32 v9, v9, v174
	v_mul_f32_e32 v10, v10, v174
	v_mul_f32_e32 v11, v11, v174
	global_load_dwordx4 v[152:155], v205, s[40:41]
	v_mul_f32_e32 v12, v12, v174
	v_mul_f32_e32 v13, v13, v174
	v_mul_f32_e32 v14, v14, v174
	v_mul_f32_e32 v15, v15, v174
	v_mul_f32_e32 v16, v16, v174
	global_load_dwordx2 v[164:165], v206, s[40:41]
	v_mul_f32_e32 v17, v17, v174
	v_mul_f32_e32 v18, v18, v174
	v_mul_f32_e32 v19, v19, v174
	v_mul_f32_e32 v20, v20, v174
	v_mul_f32_e32 v21, v21, v174
	global_load_dwordx2 v[166:167], v207, s[42:43] nt
	v_mul_f32_e32 v22, v22, v174
	v_mul_f32_e32 v23, v23, v174
	s_waitcnt lgkmcnt(12)
	v_mfma_f32_16x16x32_bf16 v[8:11], v[96:99], v[112:115], v[8:11]
	s_waitcnt lgkmcnt(10)
	v_mfma_f32_16x16x32_bf16 v[12:15], v[96:99], v[124:127], v[12:15]
	v_mfma_f32_16x16x32_bf16 v[16:19], v[104:107], v[112:115], v[16:19]
	v_mfma_f32_16x16x32_bf16 v[20:23], v[104:107], v[124:127], v[20:23]
	global_load_dword v118, v208, s[44:45]
	s_waitcnt lgkmcnt(8)
	v_mfma_f32_16x16x32_bf16 v[8:11], v[100:103], v[120:123], v[8:11]
	s_waitcnt lgkmcnt(6)
	v_mfma_f32_16x16x32_bf16 v[12:15], v[100:103], v[128:131], v[12:15]
	v_mfma_f32_16x16x32_bf16 v[16:19], v[108:111], v[120:123], v[16:19]
	v_mfma_f32_16x16x32_bf16 v[20:23], v[108:111], v[128:131], v[20:23]
	ds_read_b128 v[96:99], v232 offset:256
	global_load_dword v168, v208, s[46:47]
	ds_read_b64 v[124:125], v236 offset:43008
	ds_read_b64 v[126:127], v236 offset:47616
	s_waitcnt lgkmcnt(8)
	v_mfma_f32_16x16x32_bf16 v[48:51], v[64:67], v[28:31], 0
	s_waitcnt lgkmcnt(7)
	v_mfma_f32_16x16x32_bf16 v[48:51], v[68:71], v[32:35], v[48:51]
	s_waitcnt lgkmcnt(6)
	v_mfma_f32_16x16x32_bf16 v[48:51], v[72:75], v[40:43], v[48:51]
	global_load_dword v169, v209, s[46:47]
	s_waitcnt lgkmcnt(5)
	v_mfma_f32_16x16x32_bf16 v[48:51], v[76:79], v[44:47], v[48:51]
	v_exp_f32_e32 v195, v194
	s_nop 0
	v_mul_f32_e32 v24, v24, v195
	v_mul_f32_e32 v25, v25, v195
	v_mul_f32_e32 v26, v26, v195
	v_mul_f32_e32 v27, v27, v195
	s_add_u32 s66, s54, 3
	s_cmp_lt_u32 s66, s39
	s_cselect_b32 s74, 0xc0000, 0
	s_cselect_b32 s75, 0x280000, 0
	s_cselect_b32 s76, 0x4000, 0
	s_add_u32 s40, s40, s74
	s_addc_u32 s41, s41, 0
	s_add_u32 s42, s42, s75
	s_addc_u32 s43, s43, 0
	s_add_u32 s44, s44, s76
	s_addc_u32 s45, s45, 0
	s_add_u32 s46, s46, s76
	s_addc_u32 s47, s47, 0
	v_cvt_pk_bf16_f32 v184, v8, v9
	s_waitcnt vmcnt(10)
	v_cvt_pk_bf16_f32 v185, v10, v11
	v_cvt_pk_bf16_f32 v186, v12, v13
	ds_write_b128 v212, v[140:143]
	v_cvt_pk_bf16_f32 v187, v14, v15
	v_cvt_pk_bf16_f32 v188, v16, v17
	ds_write_b128 v212, v[144:147] offset:8192
	v_cvt_pk_bf16_f32 v189, v18, v19
	v_cvt_pk_bf16_f32 v190, v20, v21
	ds_write_b128 v212, v[132:135] offset:16384
	v_cvt_pk_bf16_f32 v191, v22, v23
	ds_write_b64 v248, v[184:185]
	ds_write_b128 v212, v[136:139] offset:24576
	ds_write_b64 v248, v[186:187] offset:4096
	v_sub_f32_e32 v200, v117, v116
	ds_write_b64 v249, v[188:189]
	ds_write_b64 v249, v[190:191] offset:4096
	v_mul_f32_e32 v200, 0x3fb8aa3b, v200
	s_waitcnt lgkmcnt(8)
	v_lshlrev_b32_e32 v112, 16, v126
	v_and_b32_e32 v113, 0xffff0000, v126
	v_exp_f32_e32 v200, v200
	v_lshlrev_b32_e32 v114, 16, v127
	v_and_b32_e32 v115, 0xffff0000, v127
	v_lshlrev_b32_e32 v196, 16, v4
	v_mul_f32_e32 v120, 0xbfb8aa3b, v112
	v_and_b32_e32 v197, 0xffff0000, v4
	v_mul_f32_e32 v121, 0xbfb8aa3b, v113
	v_mul_f32_e32 v122, 0xbfb8aa3b, v114
	v_lshlrev_b32_e32 v198, 16, v5
	v_mul_f32_e32 v123, 0xbfb8aa3b, v115
	v_exp_f32_e32 v120, v120
	v_and_b32_e32 v199, 0xffff0000, v5
	v_exp_f32_e32 v121, v121
	v_exp_f32_e32 v122, v122
	v_mul_f32_e32 v196, v196, v6
	v_exp_f32_e32 v123, v123
	v_add_f32_e32 v120, 1.0, v120
	v_mul_f32_e32 v197, v197, v6
	v_add_f32_e32 v121, 1.0, v121
	v_mul_f32_e32 v198, v198, v6
	v_add_f32_e32 v122, 1.0, v122
	v_add_f32_e32 v123, 1.0, v123
	v_mul_f32_e32 v199, v199, v6
	v_rcp_f32_e32 v120, v120
	v_rcp_f32_e32 v121, v121
	v_cvt_pk_bf16_f32 v202, v196, v197
	v_rcp_f32_e32 v122, v122
	v_rcp_f32_e32 v123, v123
	v_cvt_pk_bf16_f32 v203, v198, v199
	v_mul_f32_e32 v112, v120, v112
	v_mul_f32_e32 v113, v121, v113
	ds_write_b64 v214, v[202:203] offset:32768
	v_mul_f32_e32 v114, v122, v114
	v_mul_f32_e32 v196, v196, v200
	v_mul_f32_e32 v115, v123, v115
	v_lshlrev_b32_e32 v120, 16, v124
	v_mul_f32_e32 v197, v197, v200
	v_and_b32_e32 v121, 0xffff0000, v124
	v_lshlrev_b32_e32 v122, 16, v125
	v_mul_f32_e32 v198, v198, v200
	v_and_b32_e32 v123, 0xffff0000, v125
	v_sub_f32_e32 v184, v194, v96
	v_mul_f32_e32 v199, v199, v200
	v_sub_f32_e32 v185, v194, v97
	v_cvt_pk_bf16_f32 v192, v196, v197
	v_sub_f32_e32 v186, v194, v98
	v_sub_f32_e32 v187, v194, v99
	v_cvt_pk_bf16_f32 v193, v198, v199
	v_exp_f32_e32 v184, v184
	v_exp_f32_e32 v185, v185
	ds_write_b64 v214, v[192:193] offset:37888
	v_exp_f32_e32 v186, v186
	v_exp_f32_e32 v187, v187
	ds_write_b64 v216, v[4:5] offset:43008
	v_mul_f32_e32 v184, v48, v184
	v_mul_f32_e32 v185, v49, v185
	ds_write_b64 v216, v[36:37] offset:47616
	v_mul_f32_e32 v186, v50, v186
	v_mul_f32_e32 v201, 0x3fb8aa3b, v116
	v_mul_f32_e32 v187, v51, v187
	v_cndmask_b32_e64 v184, 0, v184, s[14:15]
	ds_write_b32 v218, v201
	v_cndmask_b32_e64 v185, 0, v185, s[16:17]
	v_cndmask_b32_e64 v186, 0, v186, s[22:23]
	v_mul_f32_e32 v174, 0x3fb8aa3b, v117
	v_cndmask_b32_e64 v187, 0, v187, s[34:35]
	v_cvt_pk_bf16_f32 v128, v184, v185
	v_exp_f32_e32 v174, v174
	v_cvt_pk_bf16_f32 v129, v186, v187
	v_mov_b32_e32 v130, 0
	v_mov_b32_e32 v131, 0
	s_nop 1
	v_mfma_f32_16x16x32_bf16 v[24:27], v[56:59], v[128:131], v[24:27]
	s_mul_i32 s65, s56, 0x2000
	s_add_u32 s65, s65, 0x304f1000
	s_add_u32 s48, s0, s65
	s_addc_u32 s49, s1, 0
	s_nop 3
	v_fma_f32 v184, s61, v120, v24
	v_fma_f32 v185, s61, v121, v25
	v_fma_f32 v186, s61, v122, v26
	v_fma_f32 v187, s61, v123, v27
	v_mul_f32_e32 v184, v184, v112
	v_mul_f32_e32 v185, v185, v113
	v_mul_f32_e32 v186, v186, v114
	v_mul_f32_e32 v187, v187, v115
	v_cvt_pk_bf16_f32 v170, v184, v185
	v_cvt_pk_bf16_f32 v171, v186, v187
	global_store_dwordx2 v210, v[170:171], s[48:49]
	s_add_u32 s65, s54, 1
	s_sub_u32 s65, s65, s60
	s_lshl_b32 s65, s65, 6
	s_add_u32 s56, s65, s20
	s_waitcnt lgkmcnt(0)
	s_barrier
	s_add_u32 s54, s54, 1
	s_cmp_lt_u32 s54, s39
	s_cbranch_scc1 .Lssd_loop0
	s_branch .Lssd_done
	.p2align	6
; __device__ __forceinline__ void phase_ssd(const Params& P, int seg, unsigned char* smem) {
;     ...
;             bf16x8 cf[4];
; #pragma unroll
;             for (int k = 0; k < 4; ++k) cf[k] = *(const bf16x8*)(sb + T_CS + (lt * 16 + fr) * 272 + (k * 32 + fq * 8) * 2);
;             f32x4 yo = {0.f, 0.f, 0.f, 0.f};
; #pragma unroll
;             for (int k = 0; k < 4; ++k) { const bf16x8 bb = *(const bf16x8*)((const unsigned char*)StR + (pt * 16 + fr) * 272 + (k * 32 + fq * 8) * 2); yo = mfma16(cf[k], bb, yo); }
; { const f32x4 a4 = *(const f32x4*)(acP + lt * 16 + fq * 4);
; #pragma unroll
;               for (int j = 0; j < 4; ++j) yo[j] *= __expf(a4[j]); }
;             const float acl_fr = acP[lt * 16 + fr]; const int lrow = lt * 16 + fr;
; #pragma unroll
;             for (int t = 0; t < 2; ++t) {
;                 if (2 * t <= lt) {
;                     v2u xb0, xb1;
;                     { const unsigned a0 = lds0 + par * T_BUF + T_XD + (32 * t + 4 * fq + tq) * 80 + (pt * 16 + 4 * tp) * 2, a1 = a0 + 16 * 80; TR_ISSUE(xb0, a0); TR_ISSUE(xb1, a1); }
;                     float m[8];
;                     { f32x4 s0 = {0.f, 0.f, 0.f, 0.f}, s1 = {0.f, 0.f, 0.f, 0.f};
; #pragma unroll
;                       for (int k = 0; k < 4; ++k) { const bf16x8 bf0 = *(const bf16x8*)(sb + T_BS + ((2 * t) * 16 + fr) * 272 + (k * 32 + fq * 8) * 2), bf1 = *(const bf16x8*)(sb + T_BS + ((2 * t + 1) * 16 + fr) * 272 + (k * 32 + fq * 8) * 2);
;                           s0 = mfma16(bf0, cf[k], s0); s1 = mfma16(bf1, cf[k], s1); }
;                       const f32x4 a0 = *(const f32x4*)(acP + (2 * t) * 16 + fq * 4), a1 = *(const f32x4*)(acP + (2 * t + 1) * 16 + fq * 4);
; #pragma unroll
;                       for (int j = 0; j < 4; ++j) { const int si0 = (2 * t) * 16 + fq * 4 + j, si1 = si0 + 16;
;                           const float e0 = s0[j] * __expf(fminf(acl_fr - a0[j], 0.f)), e1 = s1[j] * __expf(fminf(acl_fr - a1[j], 0.f));
;                           m[j] = (si0 <= lrow) ? e0 : 0.f; m[4 + j] = (si1 <= lrow) ? e1 : 0.f; } }
;                     v4u mp; mp.x = cvt_pk_bf16(m[0], m[1]); mp.y = cvt_pk_bf16(m[2], m[3]); mp.z = cvt_pk_bf16(m[4], m[5]); mp.w = cvt_pk_bf16(m[6], m[7]);
;                     asm volatile("s_waitcnt lgkmcnt(0)" : "+v"(xb0), "+v"(xb1) :: "memory");
;                     yo = mfma16(__builtin_bit_cast(bf16x8, mp), mk8(xb0, xb1), yo);
.Lssd_loop1:
	ds_read_b128 v[28:31], v219 offset:4096
	ds_read_b128 v[32:35], v220 offset:4096
	ds_read_b128 v[40:43], v221 offset:4096
	ds_read_b128 v[44:47], v222 offset:4096
	ds_read_b128 v[48:51], v227
	ds_read_b128 v[52:55], v228
	ds_read_b128 v[56:59], v229
	ds_read_b128 v[60:63], v230
	ds_read_b32 v194, v231 offset:64
	ds_read_b64_tr_b16 v[96:97], v244 offset:16384
	ds_read_b64_tr_b16 v[98:99], v244 offset:20480
	ds_read_b64_tr_b16 v[100:101], v244 offset:24576
	ds_read_b64_tr_b16 v[102:103], v244 offset:28672
	ds_read_b64_tr_b16 v[104:105], v245 offset:16384
	ds_read_b64_tr_b16 v[106:107], v245 offset:20480
	s_waitcnt lgkmcnt(11)
	ds_read_b64_tr_b16 v[108:109], v245 offset:24576
	ds_read_b64_tr_b16 v[110:111], v245 offset:28672
	ds_read_b64_tr_b16 v[112:113], v237 offset:37888
	ds_read_b64_tr_b16 v[114:115], v237 offset:39168
	s_waitcnt lgkmcnt(11)
	ds_read_b64_tr_b16 v[124:125], v237 offset:37920
	ds_read_b64_tr_b16 v[126:127], v237 offset:39200
	ds_read_b64_tr_b16 v[120:121], v237 offset:40448
	ds_read_b64_tr_b16 v[122:123], v237 offset:41728
	s_waitcnt lgkmcnt(11)
	ds_read_b64_tr_b16 v[128:129], v237 offset:40480
	ds_read_b64_tr_b16 v[130:131], v237 offset:41760
	ds_read_b128 v[64:67], v219 offset:16384
	ds_read_b128 v[68:71], v220 offset:16384
	global_load_dwordx4 v[140:143], v204, s[40:41] offset:2048
	s_waitcnt lgkmcnt(11)
	ds_read_b128 v[72:75], v221 offset:16384
	ds_read_b128 v[76:79], v222 offset:16384
	ds_read_b128 v[80:83], v219 offset:20480
	ds_read_b128 v[84:87], v220 offset:20480
	s_waitcnt lgkmcnt(11)
	ds_read_b128 v[88:91], v221 offset:20480
	ds_read_b128 v[92:95], v222 offset:20480
	global_load_dwordx4 v[144:147], v205, s[40:41] offset:2048
	v_mfma_f32_16x16x32_bf16 v[24:27], v[48:51], v[28:31], 0
	v_mfma_f32_16x16x32_bf16 v[24:27], v[52:55], v[32:35], v[24:27]
	v_mfma_f32_16x16x32_bf16 v[24:27], v[56:59], v[40:43], v[24:27]
	v_mfma_f32_16x16x32_bf16 v[24:27], v[60:63], v[44:47], v[24:27]
	ds_read_b64_tr_b16 v[56:57], v233 offset:32768
	ds_read_b64_tr_b16 v[58:59], v233 offset:34048
	global_load_dwordx4 v[132:135], v204, s[40:41]
	v_mul_f32_e32 v8, v8, v174
	v_mul_f32_e32 v9, v9, v174
	v_mul_f32_e32 v10, v10, v174
	v_mul_f32_e32 v11, v11, v174
	v_mul_f32_e32 v12, v12, v174
	v_mul_f32_e32 v13, v13, v174
	global_load_dwordx4 v[136:139], v205, s[40:41]
	v_mul_f32_e32 v14, v14, v174
	v_mul_f32_e32 v15, v15, v174
	v_mul_f32_e32 v16, v16, v174
	v_mul_f32_e32 v17, v17, v174
	v_mul_f32_e32 v18, v18, v174
	v_mul_f32_e32 v19, v19, v174
	global_load_dwordx2 v[4:5], v206, s[40:41]
	v_mul_f32_e32 v20, v20, v174
	v_mul_f32_e32 v21, v21, v174
	v_mul_f32_e32 v22, v22, v174
	v_mul_f32_e32 v23, v23, v174
	v_mfma_f32_16x16x32_bf16 v[8:11], v[96:99], v[112:115], v[8:11]
	s_waitcnt lgkmcnt(14)
	v_mfma_f32_16x16x32_bf16 v[12:15], v[96:99], v[124:127], v[12:15]
	v_mfma_f32_16x16x32_bf16 v[16:19], v[104:107], v[112:115], v[16:19]
	global_load_dwordx2 v[36:37], v207, s[42:43] nt
	v_mfma_f32_16x16x32_bf16 v[20:23], v[104:107], v[124:127], v[20:23]
	s_waitcnt lgkmcnt(12)
	v_mfma_f32_16x16x32_bf16 v[8:11], v[100:103], v[120:123], v[8:11]
	s_waitcnt lgkmcnt(10)
	v_mfma_f32_16x16x32_bf16 v[12:15], v[100:103], v[128:131], v[12:15]
	v_mfma_f32_16x16x32_bf16 v[16:19], v[108:111], v[120:123], v[16:19]
	v_mfma_f32_16x16x32_bf16 v[20:23], v[108:111], v[128:131], v[20:23]
	ds_read_b128 v[96:99], v232
	global_load_dword v6, v208, s[44:45]
	ds_read_b128 v[100:103], v232 offset:64
	ds_read_b64 v[124:125], v235 offset:44160
	ds_read_b64 v[126:127], v235 offset:48768
	s_waitcnt lgkmcnt(13)
	v_mfma_f32_16x16x32_bf16 v[48:51], v[64:67], v[28:31], 0
	s_waitcnt lgkmcnt(9)
	v_mfma_f32_16x16x32_bf16 v[52:55], v[80:83], v[28:31], 0
	v_mfma_f32_16x16x32_bf16 v[48:51], v[68:71], v[32:35], v[48:51]
	global_load_dword v116, v208, s[46:47]
	s_waitcnt lgkmcnt(8)
	v_mfma_f32_16x16x32_bf16 v[52:55], v[84:87], v[32:35], v[52:55]
	v_mfma_f32_16x16x32_bf16 v[48:51], v[72:75], v[40:43], v[48:51]
	s_waitcnt lgkmcnt(7)
	v_mfma_f32_16x16x32_bf16 v[52:55], v[88:91], v[40:43], v[52:55]
	v_mfma_f32_16x16x32_bf16 v[48:51], v[76:79], v[44:47], v[48:51]
	s_waitcnt lgkmcnt(6)
	v_mfma_f32_16x16x32_bf16 v[52:55], v[92:95], v[44:47], v[52:55]
	v_exp_f32_e32 v195, v194
	global_load_dword v117, v209, s[46:47]
	v_mul_f32_e32 v24, v24, v195
	v_mul_f32_e32 v25, v25, v195
	v_mul_f32_e32 v26, v26, v195
	v_mul_f32_e32 v27, v27, v195
	v_cvt_pk_bf16_f32 v184, v8, v9
	v_cvt_pk_bf16_f32 v185, v10, v11
	s_add_u32 s66, s54, 3
	s_cmp_lt_u32 s66, s39
	s_cselect_b32 s74, 0xc0000, 0
	s_cselect_b32 s75, 0x280000, 0
	s_cselect_b32 s76, 0x4000, 0
	s_add_u32 s40, s40, s74
	s_addc_u32 s41, s41, 0
	s_add_u32 s42, s42, s75
	s_addc_u32 s43, s43, 0
	s_add_u32 s44, s44, s76
	s_addc_u32 s45, s45, 0
	s_add_u32 s46, s46, s76
	s_addc_u32 s47, s47, 0
	v_cvt_pk_bf16_f32 v186, v12, v13
	v_cvt_pk_bf16_f32 v187, v14, v15
	s_waitcnt vmcnt(10)
	v_cvt_pk_bf16_f32 v188, v16, v17
	v_cvt_pk_bf16_f32 v189, v18, v19
	ds_write_b128 v213, v[156:159]
	v_cvt_pk_bf16_f32 v190, v20, v21
	v_cvt_pk_bf16_f32 v191, v22, v23
	ds_write_b64 v248, v[184:185] offset:8192
	ds_write_b128 v213, v[160:163] offset:8192
	ds_write_b64 v248, v[186:187] offset:12288
	ds_write_b64 v249, v[188:189] offset:8192
	ds_write_b128 v213, v[148:151] offset:16384
	ds_write_b64 v249, v[190:191] offset:12288
	s_waitcnt lgkmcnt(7)
; __device__ __forceinline__ unsigned cvt_pk_bf16(float lo, float hi) { unsigned r; asm volatile("v_cvt_pk_bf16_f32 %0, %1, %2" : "=v"(r) : "v"(lo), "v"(hi)); return r; }
; __device__ __forceinline__ void phase_ssd(const Params& P, int seg, unsigned char* smem) {
;     ...
;               for (int i = 0; i < 2; ++i) { const int q = tid + 512 * i, l = q >> 4, c8 = q & 15; *(v4u*)(sb + T_CS + l * 272 + c8 * 16) = R.Cr[i]; *(v4u*)(sb + T_BS + l * 272 + c8 * 16) = R.Br[i]; }
;               const int l = tid >> 3, p4 = (tid & 7) * 4;
;               const float x0 = bflo(R.Xr.x) * R.dtl, x1 = bfhi(R.Xr.x) * R.dtl, x2 = bflo(R.Xr.y) * R.dtl, x3 = bfhi(R.Xr.y) * R.dtl;
;               v2u d; d.x = cvt_pk_bf16(x0, x1); d.y = cvt_pk_bf16(x2, x3); *(v2u*)(sb + T_XD + l * 80 + p4 * 2) = d;
;               v2u e; e.x = cvt_pk_bf16(x0 * e2, x1 * e2); e.y = cvt_pk_bf16(x2 * e2, x3 * e2); *(v2u*)(sb + T_XE + l * 80 + p4 * 2) = e;
;               *(v2u*)(sb + T_XS + l * 64 + p4 * 2) = R.Xr; *(v2u*)(sb + T_ZS + l * 64 + p4 * 2) = R.Zr;
;               if (w == 0) acP[lane] = R.aclane; }
;     ...
;                       const f32x4 a0 = *(const f32x4*)(acP + (2 * t) * 16 + fq * 4), a1 = *(const f32x4*)(acP + (2 * t + 1) * 16 + fq * 4);
; #pragma unroll
;                       for (int j = 0; j < 4; ++j) { const int si0 = (2 * t) * 16 + fq * 4 + j, si1 = si0 + 16;
;                           const float e0 = s0[j] * __expf(fminf(acl_fr - a0[j], 0.f)), e1 = s1[j] * __expf(fminf(acl_fr - a1[j], 0.f));
;                           m[j] = (si0 <= lrow) ? e0 : 0.f; m[4 + j] = (si1 <= lrow) ? e1 : 0.f; } }
;                     v4u mp; mp.x = cvt_pk_bf16(m[0], m[1]); mp.y = cvt_pk_bf16(m[2], m[3]); mp.z = cvt_pk_bf16(m[4], m[5]); mp.w = cvt_pk_bf16(m[6], m[7]);
;                     asm volatile("s_waitcnt lgkmcnt(0)" : "+v"(xb0), "+v"(xb1) :: "memory");
;                     yo = mfma16(__builtin_bit_cast(bf16x8, mp), mk8(xb0, xb1), yo);
;                 }
;             }
; #pragma unroll
;             for (int j = 0; j < 4; ++j) { const int l = lt * 16 + fq * 4 + j, p = pt * 16 + fr; const float xv = bf2f(*(const bf16*)(sb + T_XS + l * 64 + p * 2)), zv = bf2f(*(const bf16*)(sb + T_ZS + l * 64 + p * 2));
;                 ypre[(size_t)(row0 + l) * DINNER + h * 64 + ph * 32 + p] = f2bfh((yo[j] + Dh * xv) * siluf_(zv)); }
	v_lshlrev_b32_e32 v112, 16, v126
	ds_write_b128 v213, v[152:155] offset:24576
	v_and_b32_e32 v113, 0xffff0000, v126
	v_lshlrev_b32_e32 v114, 16, v127
	v_sub_f32_e32 v200, v169, v168
	v_and_b32_e32 v115, 0xffff0000, v127
	v_mul_f32_e32 v120, 0xbfb8aa3b, v112
	v_mul_f32_e32 v200, 0x3fb8aa3b, v200
	v_mul_f32_e32 v121, 0xbfb8aa3b, v113
	v_mul_f32_e32 v122, 0xbfb8aa3b, v114
	v_exp_f32_e32 v200, v200
	v_mul_f32_e32 v123, 0xbfb8aa3b, v115
	v_exp_f32_e32 v120, v120
	v_lshlrev_b32_e32 v196, 16, v164
	v_exp_f32_e32 v121, v121
	v_exp_f32_e32 v122, v122
	v_and_b32_e32 v197, 0xffff0000, v164
	v_exp_f32_e32 v123, v123
	v_add_f32_e32 v120, 1.0, v120
	v_lshlrev_b32_e32 v198, 16, v165
	v_add_f32_e32 v121, 1.0, v121
	v_add_f32_e32 v122, 1.0, v122
	v_and_b32_e32 v199, 0xffff0000, v165
	v_add_f32_e32 v123, 1.0, v123
	v_rcp_f32_e32 v120, v120
	v_mul_f32_e32 v196, v196, v118
	v_rcp_f32_e32 v121, v121
	v_rcp_f32_e32 v122, v122
	v_mul_f32_e32 v197, v197, v118
	v_rcp_f32_e32 v123, v123
	v_mul_f32_e32 v112, v120, v112
	v_mul_f32_e32 v198, v198, v118
	v_mul_f32_e32 v113, v121, v113
	v_mul_f32_e32 v114, v122, v114
	v_mul_f32_e32 v199, v199, v118
	v_mul_f32_e32 v115, v123, v115
	v_lshlrev_b32_e32 v120, 16, v124
	v_cvt_pk_bf16_f32 v202, v196, v197
	v_and_b32_e32 v121, 0xffff0000, v124
	v_lshlrev_b32_e32 v122, 16, v125
	v_and_b32_e32 v123, 0xffff0000, v125
	v_cvt_pk_bf16_f32 v203, v198, v199
	v_sub_f32_e32 v184, v194, v96
	v_sub_f32_e32 v185, v194, v97
	ds_write_b64 v215, v[202:203] offset:32768
	v_sub_f32_e32 v186, v194, v98
	v_sub_f32_e32 v187, v194, v99
	v_mul_f32_e32 v196, v196, v200
	v_exp_f32_e32 v184, v184
	v_exp_f32_e32 v185, v185
	v_mul_f32_e32 v197, v197, v200
	v_exp_f32_e32 v186, v186
	v_exp_f32_e32 v187, v187
	v_mul_f32_e32 v198, v198, v200
	v_mul_f32_e32 v184, v48, v184
	v_mul_f32_e32 v185, v49, v185
	v_mul_f32_e32 v199, v199, v200
	v_mul_f32_e32 v186, v50, v186
	v_mul_f32_e32 v187, v51, v187
	v_cvt_pk_bf16_f32 v192, v196, v197
	v_sub_f32_e32 v188, v194, v100
	v_sub_f32_e32 v189, v194, v101
	v_cvt_pk_bf16_f32 v193, v198, v199
	v_sub_f32_e32 v190, v194, v102
	v_sub_f32_e32 v191, v194, v103
	ds_write_b64 v215, v[192:193] offset:37888
	v_exp_f32_e32 v188, v188
	v_exp_f32_e32 v189, v189
	ds_write_b64 v217, v[164:165] offset:43008
	v_exp_f32_e32 v190, v190
	v_exp_f32_e32 v191, v191
	ds_write_b64 v217, v[166:167] offset:47616
	v_mul_f32_e32 v188, v52, v188
	v_mul_f32_e32 v189, v53, v189
	v_mul_f32_e32 v201, 0x3fb8aa3b, v168
	v_mul_f32_e32 v190, v54, v190
	v_mul_f32_e32 v191, v55, v191
	ds_write_b32 v218, v201 offset:256
	v_cndmask_b32_e64 v188, 0, v188, s[14:15]
	v_cndmask_b32_e64 v189, 0, v189, s[16:17]
	v_mul_f32_e32 v174, 0x3fb8aa3b, v169
	v_cndmask_b32_e64 v190, 0, v190, s[22:23]
	v_cndmask_b32_e64 v191, 0, v191, s[34:35]
	v_exp_f32_e32 v174, v174
	v_cvt_pk_bf16_f32 v128, v184, v185
	v_cvt_pk_bf16_f32 v129, v186, v187
	v_cvt_pk_bf16_f32 v130, v188, v189
	v_cvt_pk_bf16_f32 v131, v190, v191
	s_nop 1
	v_mfma_f32_16x16x32_bf16 v[24:27], v[56:59], v[128:131], v[24:27]
	s_mul_i32 s65, s56, 0x2000
	s_add_u32 s65, s65, 0x304f1000
	s_add_u32 s48, s0, s65
	s_addc_u32 s49, s1, 0
	s_nop 3
	v_fma_f32 v184, s61, v120, v24
	v_fma_f32 v185, s61, v121, v25
	v_fma_f32 v186, s61, v122, v26
	v_fma_f32 v187, s61, v123, v27
	v_mul_f32_e32 v184, v184, v112
	v_mul_f32_e32 v185, v185, v113
	v_mul_f32_e32 v186, v186, v114
	v_mul_f32_e32 v187, v187, v115
	v_cvt_pk_bf16_f32 v170, v184, v185
	v_cvt_pk_bf16_f32 v171, v186, v187
	global_store_dwordx2 v210, v[170:171], s[48:49]
	s_add_u32 s65, s54, 1
	s_sub_u32 s65, s65, s60
	s_lshl_b32 s65, s65, 6
	s_add_u32 s56, s65, s20
	s_waitcnt lgkmcnt(0)
	s_barrier
	s_add_u32 s54, s54, 1
	s_cmp_ge_u32 s54, s39
	s_cbranch_scc1 .Lssd_done
	ds_read_b128 v[28:31], v223 offset:4096
	ds_read_b128 v[32:35], v224 offset:4096
	ds_read_b128 v[40:43], v225 offset:4096
	ds_read_b128 v[44:47], v226 offset:4096
	ds_read_b128 v[48:51], v227 offset:8192
	ds_read_b128 v[52:55], v228 offset:8192
	ds_read_b128 v[56:59], v229 offset:8192
	ds_read_b128 v[60:63], v230 offset:8192
	ds_read_b32 v194, v231 offset:320
	ds_read_b64_tr_b16 v[96:97], v246 offset:16384
	ds_read_b64_tr_b16 v[98:99], v246 offset:20480
	ds_read_b64_tr_b16 v[100:101], v246 offset:24576
	ds_read_b64_tr_b16 v[102:103], v246 offset:28672
	ds_read_b64_tr_b16 v[104:105], v247 offset:16384
	ds_read_b64_tr_b16 v[106:107], v247 offset:20480
	s_waitcnt lgkmcnt(11)
	ds_read_b64_tr_b16 v[108:109], v247 offset:24576
	ds_read_b64_tr_b16 v[110:111], v247 offset:28672
	ds_read_b64_tr_b16 v[112:113], v243 offset:37888
	ds_read_b64_tr_b16 v[114:115], v243 offset:39168
	s_waitcnt lgkmcnt(11)
	ds_read_b64_tr_b16 v[124:125], v243 offset:37920
	ds_read_b64_tr_b16 v[126:127], v243 offset:39200
	ds_read_b64_tr_b16 v[120:121], v243 offset:40448
	ds_read_b64_tr_b16 v[122:123], v243 offset:41728
	s_waitcnt lgkmcnt(11)
	ds_read_b64_tr_b16 v[128:129], v243 offset:40480
	ds_read_b64_tr_b16 v[130:131], v243 offset:41760
	ds_read_b128 v[64:67], v223 offset:16384
	ds_read_b128 v[68:71], v224 offset:16384
	global_load_dwordx4 v[156:159], v204, s[40:41] offset:2048
	s_waitcnt lgkmcnt(11)
	ds_read_b128 v[72:75], v225 offset:16384
	ds_read_b128 v[76:79], v226 offset:16384
	ds_read_b128 v[80:83], v223 offset:20480
	ds_read_b128 v[84:87], v224 offset:20480
	s_waitcnt lgkmcnt(11)
; __device__ __forceinline__ void phase_ssd(const Params& P, int seg, unsigned char* smem) {
;     ...
;             bf16x8 cf[4];
; #pragma unroll
;             for (int k = 0; k < 4; ++k) cf[k] = *(const bf16x8*)(sb + T_CS + (lt * 16 + fr) * 272 + (k * 32 + fq * 8) * 2);
;             f32x4 yo = {0.f, 0.f, 0.f, 0.f};
; #pragma unroll
;             for (int k = 0; k < 4; ++k) { const bf16x8 bb = *(const bf16x8*)((const unsigned char*)StR + (pt * 16 + fr) * 272 + (k * 32 + fq * 8) * 2); yo = mfma16(cf[k], bb, yo); }
; { const f32x4 a4 = *(const f32x4*)(acP + lt * 16 + fq * 4);
; #pragma unroll
;               for (int j = 0; j < 4; ++j) yo[j] *= __expf(a4[j]); }
;             const float acl_fr = acP[lt * 16 + fr]; const int lrow = lt * 16 + fr;
; #pragma unroll
;             for (int t = 0; t < 2; ++t) {
;                 if (2 * t <= lt) {
;                     v2u xb0, xb1;
;                     { const unsigned a0 = lds0 + par * T_BUF + T_XD + (32 * t + 4 * fq + tq) * 80 + (pt * 16 + 4 * tp) * 2, a1 = a0 + 16 * 80; TR_ISSUE(xb0, a0); TR_ISSUE(xb1, a1); }
;                     float m[8];
;                     { f32x4 s0 = {0.f, 0.f, 0.f, 0.f}, s1 = {0.f, 0.f, 0.f, 0.f};
; #pragma unroll
;                       for (int k = 0; k < 4; ++k) { const bf16x8 bf0 = *(const bf16x8*)(sb + T_BS + ((2 * t) * 16 + fr) * 272 + (k * 32 + fq * 8) * 2), bf1 = *(const bf16x8*)(sb + T_BS + ((2 * t + 1) * 16 + fr) * 272 + (k * 32 + fq * 8) * 2);
;                           s0 = mfma16(bf0, cf[k], s0); s1 = mfma16(bf1, cf[k], s1); }
;                       const f32x4 a0 = *(const f32x4*)(acP + (2 * t) * 16 + fq * 4), a1 = *(const f32x4*)(acP + (2 * t + 1) * 16 + fq * 4);
; #pragma unroll
;                       for (int j = 0; j < 4; ++j) { const int si0 = (2 * t) * 16 + fq * 4 + j, si1 = si0 + 16;
;                           const float e0 = s0[j] * __expf(fminf(acl_fr - a0[j], 0.f)), e1 = s1[j] * __expf(fminf(acl_fr - a1[j], 0.f));
;                           m[j] = (si0 <= lrow) ? e0 : 0.f; m[4 + j] = (si1 <= lrow) ? e1 : 0.f; } }
;                     v4u mp; mp.x = cvt_pk_bf16(m[0], m[1]); mp.y = cvt_pk_bf16(m[2], m[3]); mp.z = cvt_pk_bf16(m[4], m[5]); mp.w = cvt_pk_bf16(m[6], m[7]);
;                     asm volatile("s_waitcnt lgkmcnt(0)" : "+v"(xb0), "+v"(xb1) :: "memory");
;                     yo = mfma16(__builtin_bit_cast(bf16x8, mp), mk8(xb0, xb1), yo);
	ds_read_b128 v[88:91], v225 offset:20480
	ds_read_b128 v[92:95], v226 offset:20480
	global_load_dwordx4 v[160:163], v205, s[40:41] offset:2048
	v_mfma_f32_16x16x32_bf16 v[24:27], v[48:51], v[28:31], 0
	v_mfma_f32_16x16x32_bf16 v[24:27], v[52:55], v[32:35], v[24:27]
	v_mfma_f32_16x16x32_bf16 v[24:27], v[56:59], v[40:43], v[24:27]
	v_mfma_f32_16x16x32_bf16 v[24:27], v[60:63], v[44:47], v[24:27]
	ds_read_b64_tr_b16 v[56:57], v234 offset:32768
	ds_read_b64_tr_b16 v[58:59], v234 offset:34048
	global_load_dwordx4 v[148:151], v204, s[40:41]
	v_mul_f32_e32 v8, v8, v174
	v_mul_f32_e32 v9, v9, v174
	v_mul_f32_e32 v10, v10, v174
	v_mul_f32_e32 v11, v11, v174
	v_mul_f32_e32 v12, v12, v174
	v_mul_f32_e32 v13, v13, v174
	global_load_dwordx4 v[152:155], v205, s[40:41]
	v_mul_f32_e32 v14, v14, v174
	v_mul_f32_e32 v15, v15, v174
	v_mul_f32_e32 v16, v16, v174
	v_mul_f32_e32 v17, v17, v174
	v_mul_f32_e32 v18, v18, v174
	v_mul_f32_e32 v19, v19, v174
	global_load_dwordx2 v[164:165], v206, s[40:41]
	v_mul_f32_e32 v20, v20, v174
	v_mul_f32_e32 v21, v21, v174
	v_mul_f32_e32 v22, v22, v174
	v_mul_f32_e32 v23, v23, v174
	v_mfma_f32_16x16x32_bf16 v[8:11], v[96:99], v[112:115], v[8:11]
	s_waitcnt lgkmcnt(14)
	v_mfma_f32_16x16x32_bf16 v[12:15], v[96:99], v[124:127], v[12:15]
	v_mfma_f32_16x16x32_bf16 v[16:19], v[104:107], v[112:115], v[16:19]
	global_load_dwordx2 v[166:167], v207, s[42:43] nt
	v_mfma_f32_16x16x32_bf16 v[20:23], v[104:107], v[124:127], v[20:23]
	s_waitcnt lgkmcnt(12)
	v_mfma_f32_16x16x32_bf16 v[8:11], v[100:103], v[120:123], v[8:11]
	s_waitcnt lgkmcnt(10)
	v_mfma_f32_16x16x32_bf16 v[12:15], v[100:103], v[128:131], v[12:15]
	v_mfma_f32_16x16x32_bf16 v[16:19], v[108:111], v[120:123], v[16:19]
	v_mfma_f32_16x16x32_bf16 v[20:23], v[108:111], v[128:131], v[20:23]
	ds_read_b128 v[96:99], v232 offset:256
	global_load_dword v118, v208, s[44:45]
	ds_read_b128 v[100:103], v232 offset:320
	ds_read_b64 v[124:125], v236 offset:44160
	ds_read_b64 v[126:127], v236 offset:48768
	s_waitcnt lgkmcnt(13)
	v_mfma_f32_16x16x32_bf16 v[48:51], v[64:67], v[28:31], 0
	s_waitcnt lgkmcnt(9)
	v_mfma_f32_16x16x32_bf16 v[52:55], v[80:83], v[28:31], 0
	v_mfma_f32_16x16x32_bf16 v[48:51], v[68:71], v[32:35], v[48:51]
	global_load_dword v168, v208, s[46:47]
	s_waitcnt lgkmcnt(8)
	v_mfma_f32_16x16x32_bf16 v[52:55], v[84:87], v[32:35], v[52:55]
	v_mfma_f32_16x16x32_bf16 v[48:51], v[72:75], v[40:43], v[48:51]
	s_waitcnt lgkmcnt(7)
	v_mfma_f32_16x16x32_bf16 v[52:55], v[88:91], v[40:43], v[52:55]
	v_mfma_f32_16x16x32_bf16 v[48:51], v[76:79], v[44:47], v[48:51]
	s_waitcnt lgkmcnt(6)
	v_mfma_f32_16x16x32_bf16 v[52:55], v[92:95], v[44:47], v[52:55]
	v_exp_f32_e32 v195, v194
	global_load_dword v169, v209, s[46:47]
	v_mul_f32_e32 v24, v24, v195
	v_mul_f32_e32 v25, v25, v195
	v_mul_f32_e32 v26, v26, v195
	v_mul_f32_e32 v27, v27, v195
	v_cvt_pk_bf16_f32 v184, v8, v9
	v_cvt_pk_bf16_f32 v185, v10, v11
	s_add_u32 s66, s54, 3
	s_cmp_lt_u32 s66, s39
	s_cselect_b32 s74, 0xc0000, 0
	s_cselect_b32 s75, 0x280000, 0
	s_cselect_b32 s76, 0x4000, 0
	s_add_u32 s40, s40, s74
	s_addc_u32 s41, s41, 0
	s_add_u32 s42, s42, s75
	s_addc_u32 s43, s43, 0
	s_add_u32 s44, s44, s76
	s_addc_u32 s45, s45, 0
	s_add_u32 s46, s46, s76
	s_addc_u32 s47, s47, 0
	v_cvt_pk_bf16_f32 v186, v12, v13
	v_cvt_pk_bf16_f32 v187, v14, v15
	s_waitcnt vmcnt(10)
	v_cvt_pk_bf16_f32 v188, v16, v17
	v_cvt_pk_bf16_f32 v189, v18, v19
	ds_write_b128 v212, v[140:143]
	v_cvt_pk_bf16_f32 v190, v20, v21
	v_cvt_pk_bf16_f32 v191, v22, v23
	ds_write_b64 v248, v[184:185]
	ds_write_b128 v212, v[144:147] offset:8192
	ds_write_b64 v248, v[186:187] offset:4096
	ds_write_b64 v249, v[188:189]
	ds_write_b128 v212, v[132:135] offset:16384
	ds_write_b64 v249, v[190:191] offset:4096
	s_waitcnt lgkmcnt(7)
	v_lshlrev_b32_e32 v112, 16, v126
	ds_write_b128 v212, v[136:139] offset:24576
	v_and_b32_e32 v113, 0xffff0000, v126
	v_lshlrev_b32_e32 v114, 16, v127
	v_sub_f32_e32 v200, v117, v116
	v_and_b32_e32 v115, 0xffff0000, v127
	v_mul_f32_e32 v120, 0xbfb8aa3b, v112
	v_mul_f32_e32 v200, 0x3fb8aa3b, v200
	v_mul_f32_e32 v121, 0xbfb8aa3b, v113
	v_mul_f32_e32 v122, 0xbfb8aa3b, v114
	v_exp_f32_e32 v200, v200
	v_mul_f32_e32 v123, 0xbfb8aa3b, v115
	v_exp_f32_e32 v120, v120
	v_lshlrev_b32_e32 v196, 16, v4
	v_exp_f32_e32 v121, v121
	v_exp_f32_e32 v122, v122
	v_and_b32_e32 v197, 0xffff0000, v4
	v_exp_f32_e32 v123, v123
	v_add_f32_e32 v120, 1.0, v120
	v_lshlrev_b32_e32 v198, 16, v5
	v_add_f32_e32 v121, 1.0, v121
	v_add_f32_e32 v122, 1.0, v122
	v_and_b32_e32 v199, 0xffff0000, v5
	v_add_f32_e32 v123, 1.0, v123
	v_rcp_f32_e32 v120, v120
	v_mul_f32_e32 v196, v196, v6
	v_rcp_f32_e32 v121, v121
	v_rcp_f32_e32 v122, v122
	v_mul_f32_e32 v197, v197, v6
	v_rcp_f32_e32 v123, v123
	v_mul_f32_e32 v112, v120, v112
	v_mul_f32_e32 v198, v198, v6
	v_mul_f32_e32 v113, v121, v113
	v_mul_f32_e32 v114, v122, v114
	v_mul_f32_e32 v199, v199, v6
	v_mul_f32_e32 v115, v123, v115
	v_lshlrev_b32_e32 v120, 16, v124
	v_cvt_pk_bf16_f32 v202, v196, v197
	v_and_b32_e32 v121, 0xffff0000, v124
	v_lshlrev_b32_e32 v122, 16, v125
	v_and_b32_e32 v123, 0xffff0000, v125
	v_cvt_pk_bf16_f32 v203, v198, v199
	v_sub_f32_e32 v184, v194, v96
	v_sub_f32_e32 v185, v194, v97
	ds_write_b64 v214, v[202:203] offset:32768
	v_sub_f32_e32 v186, v194, v98
	v_sub_f32_e32 v187, v194, v99
	v_mul_f32_e32 v196, v196, v200
	v_exp_f32_e32 v184, v184
	v_exp_f32_e32 v185, v185
	v_mul_f32_e32 v197, v197, v200
	v_exp_f32_e32 v186, v186
	v_exp_f32_e32 v187, v187
	v_mul_f32_e32 v198, v198, v200
	v_mul_f32_e32 v184, v48, v184
	v_mul_f32_e32 v185, v49, v185
	v_mul_f32_e32 v199, v199, v200
	v_mul_f32_e32 v186, v50, v186
	v_mul_f32_e32 v187, v51, v187
; __device__ __forceinline__ bf16 f2bfh(float f) { return (bf16)(cvt_pk_bf16(f, f) & 0xffffu); }
; __device__ __forceinline__ void phase_ssd(const Params& P, int seg, unsigned char* smem) {
;     ...
;             bf16x8 cf[4];
; #pragma unroll
;             for (int k = 0; k < 4; ++k) cf[k] = *(const bf16x8*)(sb + T_CS + (lt * 16 + fr) * 272 + (k * 32 + fq * 8) * 2);
;             f32x4 yo = {0.f, 0.f, 0.f, 0.f};
; #pragma unroll
;             for (int k = 0; k < 4; ++k) { const bf16x8 bb = *(const bf16x8*)((const unsigned char*)StR + (pt * 16 + fr) * 272 + (k * 32 + fq * 8) * 2); yo = mfma16(cf[k], bb, yo); }
; { const f32x4 a4 = *(const f32x4*)(acP + lt * 16 + fq * 4);
; #pragma unroll
;               for (int j = 0; j < 4; ++j) yo[j] *= __expf(a4[j]); }
;             const float acl_fr = acP[lt * 16 + fr]; const int lrow = lt * 16 + fr;
; #pragma unroll
;             for (int t = 0; t < 2; ++t) {
;                 if (2 * t <= lt) {
;                     v2u xb0, xb1;
;                     { const unsigned a0 = lds0 + par * T_BUF + T_XD + (32 * t + 4 * fq + tq) * 80 + (pt * 16 + 4 * tp) * 2, a1 = a0 + 16 * 80; TR_ISSUE(xb0, a0); TR_ISSUE(xb1, a1); }
;                     float m[8];
;                     { f32x4 s0 = {0.f, 0.f, 0.f, 0.f}, s1 = {0.f, 0.f, 0.f, 0.f};
; #pragma unroll
;     ...
;                       for (int j = 0; j < 4; ++j) { const int si0 = (2 * t) * 16 + fq * 4 + j, si1 = si0 + 16;
;                           const float e0 = s0[j] * __expf(fminf(acl_fr - a0[j], 0.f)), e1 = s1[j] * __expf(fminf(acl_fr - a1[j], 0.f));
;                           m[j] = (si0 <= lrow) ? e0 : 0.f; m[4 + j] = (si1 <= lrow) ? e1 : 0.f; } }
;                     v4u mp; mp.x = cvt_pk_bf16(m[0], m[1]); mp.y = cvt_pk_bf16(m[2], m[3]); mp.z = cvt_pk_bf16(m[4], m[5]); mp.w = cvt_pk_bf16(m[6], m[7]);
;                     asm volatile("s_waitcnt lgkmcnt(0)" : "+v"(xb0), "+v"(xb1) :: "memory");
;                     yo = mfma16(__builtin_bit_cast(bf16x8, mp), mk8(xb0, xb1), yo);
;                 }
;             }
; #pragma unroll
;             for (int j = 0; j < 4; ++j) { const int l = lt * 16 + fq * 4 + j, p = pt * 16 + fr; const float xv = bf2f(*(const bf16*)(sb + T_XS + l * 64 + p * 2)), zv = bf2f(*(const bf16*)(sb + T_ZS + l * 64 + p * 2));
;                 ypre[(size_t)(row0 + l) * DINNER + h * 64 + ph * 32 + p] = f2bfh((yo[j] + Dh * xv) * siluf_(zv)); }
	v_cvt_pk_bf16_f32 v192, v196, v197
	v_sub_f32_e32 v188, v194, v100
	v_sub_f32_e32 v189, v194, v101
	v_cvt_pk_bf16_f32 v193, v198, v199
	v_sub_f32_e32 v190, v194, v102
	v_sub_f32_e32 v191, v194, v103
	ds_write_b64 v214, v[192:193] offset:37888
	v_exp_f32_e32 v188, v188
	v_exp_f32_e32 v189, v189
	ds_write_b64 v216, v[4:5] offset:43008
	v_exp_f32_e32 v190, v190
	v_exp_f32_e32 v191, v191
	ds_write_b64 v216, v[36:37] offset:47616
	v_mul_f32_e32 v188, v52, v188
	v_mul_f32_e32 v189, v53, v189
	v_mul_f32_e32 v201, 0x3fb8aa3b, v116
	v_mul_f32_e32 v190, v54, v190
	v_mul_f32_e32 v191, v55, v191
	ds_write_b32 v218, v201
	v_cndmask_b32_e64 v188, 0, v188, s[14:15]
	v_cndmask_b32_e64 v189, 0, v189, s[16:17]
	v_mul_f32_e32 v174, 0x3fb8aa3b, v117
	v_cndmask_b32_e64 v190, 0, v190, s[22:23]
	v_cndmask_b32_e64 v191, 0, v191, s[34:35]
	v_exp_f32_e32 v174, v174
	v_cvt_pk_bf16_f32 v128, v184, v185
	v_cvt_pk_bf16_f32 v129, v186, v187
	v_cvt_pk_bf16_f32 v130, v188, v189
	v_cvt_pk_bf16_f32 v131, v190, v191
	s_nop 1
	v_mfma_f32_16x16x32_bf16 v[24:27], v[56:59], v[128:131], v[24:27]
	s_mul_i32 s65, s56, 0x2000
	s_add_u32 s65, s65, 0x304f1000
	s_add_u32 s48, s0, s65
	s_addc_u32 s49, s1, 0
	s_nop 3
	v_fma_f32 v184, s61, v120, v24
	v_fma_f32 v185, s61, v121, v25
	v_fma_f32 v186, s61, v122, v26
	v_fma_f32 v187, s61, v123, v27
	v_mul_f32_e32 v184, v184, v112
	v_mul_f32_e32 v185, v185, v113
	v_mul_f32_e32 v186, v186, v114
	v_mul_f32_e32 v187, v187, v115
	v_cvt_pk_bf16_f32 v170, v184, v185
	v_cvt_pk_bf16_f32 v171, v186, v187
	global_store_dwordx2 v210, v[170:171], s[48:49]
	s_add_u32 s65, s54, 1
	s_sub_u32 s65, s65, s60
	s_lshl_b32 s65, s65, 6
	s_add_u32 s56, s65, s20
	s_waitcnt lgkmcnt(0)
	s_barrier
	s_add_u32 s54, s54, 1
	s_cmp_lt_u32 s54, s39
	s_cbranch_scc1 .Lssd_loop1
	s_branch .Lssd_done
	.p2align	6
.Lssd_loop2:
	ds_read_b128 v[28:31], v219 offset:8192
	ds_read_b128 v[32:35], v220 offset:8192
	ds_read_b128 v[40:43], v221 offset:8192
	ds_read_b128 v[44:47], v222 offset:8192
	ds_read_b128 v[48:51], v227
	ds_read_b128 v[52:55], v228
	ds_read_b128 v[56:59], v229
	ds_read_b128 v[60:63], v230
	ds_read_b32 v194, v231 offset:128
	ds_read_b128 v[64:67], v219 offset:16384
	ds_read_b128 v[68:71], v220 offset:16384
	ds_read_b128 v[72:75], v221 offset:16384
	ds_read_b128 v[76:79], v222 offset:16384
	ds_read_b128 v[80:83], v219 offset:20480
	ds_read_b128 v[84:87], v220 offset:20480
	global_load_dwordx4 v[140:143], v204, s[40:41] offset:2048
	s_waitcnt lgkmcnt(11)
	ds_read_b128 v[88:91], v221 offset:20480
	ds_read_b128 v[92:95], v222 offset:20480
	ds_read_b128 v[96:99], v232
	ds_read_b128 v[100:103], v232 offset:64
	s_waitcnt lgkmcnt(11)
	ds_read_b64 v[124:125], v235 offset:45312
	global_load_dwordx4 v[144:147], v205, s[40:41] offset:2048
	ds_read_b64 v[126:127], v235 offset:49920
	v_mfma_f32_16x16x32_bf16 v[24:27], v[48:51], v[28:31], 0
	v_mfma_f32_16x16x32_bf16 v[24:27], v[52:55], v[32:35], v[24:27]
	v_mfma_f32_16x16x32_bf16 v[24:27], v[56:59], v[40:43], v[24:27]
	v_mfma_f32_16x16x32_bf16 v[24:27], v[60:63], v[44:47], v[24:27]
	ds_read_b64_tr_b16 v[56:57], v233 offset:32768
	global_load_dwordx4 v[132:135], v204, s[40:41]
	ds_read_b64_tr_b16 v[58:59], v233 offset:34048
	s_waitcnt lgkmcnt(13)
	v_mfma_f32_16x16x32_bf16 v[48:51], v[64:67], v[28:31], 0
	s_waitcnt lgkmcnt(9)
	v_mfma_f32_16x16x32_bf16 v[52:55], v[80:83], v[28:31], 0
	v_mfma_f32_16x16x32_bf16 v[48:51], v[68:71], v[32:35], v[48:51]
	s_waitcnt lgkmcnt(8)
	v_mfma_f32_16x16x32_bf16 v[52:55], v[84:87], v[32:35], v[52:55]
	global_load_dwordx4 v[136:139], v205, s[40:41]
	v_mfma_f32_16x16x32_bf16 v[48:51], v[72:75], v[40:43], v[48:51]
	s_waitcnt lgkmcnt(7)
	v_mfma_f32_16x16x32_bf16 v[52:55], v[88:91], v[40:43], v[52:55]
	v_mfma_f32_16x16x32_bf16 v[48:51], v[76:79], v[44:47], v[48:51]
	s_waitcnt lgkmcnt(6)
	v_mfma_f32_16x16x32_bf16 v[52:55], v[92:95], v[44:47], v[52:55]
	ds_read_b128 v[64:67], v219 offset:24576
	ds_read_b128 v[68:71], v220 offset:24576
	global_load_dwordx2 v[4:5], v206, s[40:41]
	ds_read_b128 v[72:75], v221 offset:24576
	ds_read_b128 v[76:79], v222 offset:24576
	ds_read_b64_tr_b16 v[60:61], v233 offset:35328
	ds_read_b64_tr_b16 v[62:63], v233 offset:36608
	v_exp_f32_e32 v195, v194
	s_nop 0
	v_mul_f32_e32 v24, v24, v195
	global_load_dwordx2 v[36:37], v207, s[42:43] nt
	v_mul_f32_e32 v25, v25, v195
	v_mul_f32_e32 v26, v26, v195
	v_mul_f32_e32 v27, v27, v195
	s_waitcnt lgkmcnt(8)
	v_lshlrev_b32_e32 v112, 16, v126
	v_and_b32_e32 v113, 0xffff0000, v126
	global_load_dword v6, v208, s[44:45]
	v_lshlrev_b32_e32 v114, 16, v127
	v_and_b32_e32 v115, 0xffff0000, v127
	v_mul_f32_e32 v120, 0xbfb8aa3b, v112
	v_mul_f32_e32 v121, 0xbfb8aa3b, v113
	v_mul_f32_e32 v122, 0xbfb8aa3b, v114
	v_mul_f32_e32 v123, 0xbfb8aa3b, v115
	global_load_dword v116, v208, s[46:47]
	v_exp_f32_e32 v120, v120
	v_exp_f32_e32 v121, v121
	v_exp_f32_e32 v122, v122
	v_exp_f32_e32 v123, v123
	v_add_f32_e32 v120, 1.0, v120
	global_load_dword v117, v209, s[46:47]
	v_add_f32_e32 v121, 1.0, v121
	v_add_f32_e32 v122, 1.0, v122
	v_add_f32_e32 v123, 1.0, v123
	v_rcp_f32_e32 v120, v120
	v_rcp_f32_e32 v121, v121
	v_rcp_f32_e32 v122, v122
	s_add_u32 s66, s54, 3
	s_cmp_lt_u32 s66, s39
	s_cselect_b32 s74, 0xc0000, 0
	s_cselect_b32 s75, 0x280000, 0
	s_cselect_b32 s76, 0x4000, 0
	s_add_u32 s40, s40, s74
	s_addc_u32 s41, s41, 0
	s_add_u32 s42, s42, s75
	s_addc_u32 s43, s43, 0
	s_add_u32 s44, s44, s76
	s_addc_u32 s45, s45, 0
	s_add_u32 s46, s46, s76
	s_addc_u32 s47, s47, 0
	v_rcp_f32_e32 v123, v123
	v_mul_f32_e32 v112, v120, v112
	s_waitcnt vmcnt(10)
; __device__ __forceinline__ void phase_ssd(const Params& P, int seg, unsigned char* smem) {
;     ...
;               for (int i = 0; i < 2; ++i) { const int q = tid + 512 * i, l = q >> 4, c8 = q & 15; *(v4u*)(sb + T_CS + l * 272 + c8 * 16) = R.Cr[i]; *(v4u*)(sb + T_BS + l * 272 + c8 * 16) = R.Br[i]; }
;               const int l = tid >> 3, p4 = (tid & 7) * 4;
;               const float x0 = bflo(R.Xr.x) * R.dtl, x1 = bfhi(R.Xr.x) * R.dtl, x2 = bflo(R.Xr.y) * R.dtl, x3 = bfhi(R.Xr.y) * R.dtl;
;               v2u d; d.x = cvt_pk_bf16(x0, x1); d.y = cvt_pk_bf16(x2, x3); *(v2u*)(sb + T_XD + l * 80 + p4 * 2) = d;
;               v2u e; e.x = cvt_pk_bf16(x0 * e2, x1 * e2); e.y = cvt_pk_bf16(x2 * e2, x3 * e2); *(v2u*)(sb + T_XE + l * 80 + p4 * 2) = e;
;               *(v2u*)(sb + T_XS + l * 64 + p4 * 2) = R.Xr; *(v2u*)(sb + T_ZS + l * 64 + p4 * 2) = R.Zr;
;               if (w == 0) acP[lane] = R.aclane; }
;             BAR_LDS();
;             if (ci + 2 < nchunks) load_chunk(ci + 2, R);
;             bf16x8 cf[4];
; #pragma unroll
;             for (int k = 0; k < 4; ++k) cf[k] = *(const bf16x8*)(sb + T_CS + (lt * 16 + fr) * 272 + (k * 32 + fq * 8) * 2);
;             f32x4 yo = {0.f, 0.f, 0.f, 0.f};
; #pragma unroll
;             for (int k = 0; k < 4; ++k) { const bf16x8 bb = *(const bf16x8*)((const unsigned char*)StR + (pt * 16 + fr) * 272 + (k * 32 + fq * 8) * 2); yo = mfma16(cf[k], bb, yo); }
; { const f32x4 a4 = *(const f32x4*)(acP + lt * 16 + fq * 4);
; #pragma unroll
;               for (int j = 0; j < 4; ++j) yo[j] *= __expf(a4[j]); }
;             const float acl_fr = acP[lt * 16 + fr]; const int lrow = lt * 16 + fr;
; #pragma unroll
;             for (int t = 0; t < 2; ++t) {
;                 if (2 * t <= lt) {
;                     v2u xb0, xb1;
;                     { const unsigned a0 = lds0 + par * T_BUF + T_XD + (32 * t + 4 * fq + tq) * 80 + (pt * 16 + 4 * tp) * 2, a1 = a0 + 16 * 80; TR_ISSUE(xb0, a0); TR_ISSUE(xb1, a1); }
;                     float m[8];
;                     { f32x4 s0 = {0.f, 0.f, 0.f, 0.f}, s1 = {0.f, 0.f, 0.f, 0.f};
; #pragma unroll
;                       for (int k = 0; k < 4; ++k) { const bf16x8 bf0 = *(const bf16x8*)(sb + T_BS + ((2 * t) * 16 + fr) * 272 + (k * 32 + fq * 8) * 2), bf1 = *(const bf16x8*)(sb + T_BS + ((2 * t + 1) * 16 + fr) * 272 + (k * 32 + fq * 8) * 2);
	v_mul_f32_e32 v113, v121, v113
	v_mul_f32_e32 v114, v122, v114
	ds_write_b128 v213, v[156:159]
	v_mul_f32_e32 v115, v123, v115
	v_lshlrev_b32_e32 v120, 16, v124
	ds_write_b128 v213, v[160:163] offset:8192
	v_and_b32_e32 v121, 0xffff0000, v124
	ds_write_b128 v213, v[148:151] offset:16384
	v_lshlrev_b32_e32 v122, 16, v125
	v_and_b32_e32 v123, 0xffff0000, v125
	ds_write_b128 v213, v[152:155] offset:24576
	v_sub_f32_e32 v184, v194, v96
	v_sub_f32_e32 v185, v194, v97
	v_sub_f32_e32 v200, v169, v168
	v_sub_f32_e32 v186, v194, v98
	v_sub_f32_e32 v187, v194, v99
	v_mul_f32_e32 v200, 0x3fb8aa3b, v200
	v_exp_f32_e32 v184, v184
	v_exp_f32_e32 v185, v185
	v_exp_f32_e32 v200, v200
	v_exp_f32_e32 v186, v186
	v_exp_f32_e32 v187, v187
	v_lshlrev_b32_e32 v196, 16, v164
	v_mul_f32_e32 v184, v48, v184
	v_mul_f32_e32 v185, v49, v185
	v_and_b32_e32 v197, 0xffff0000, v164
	v_mul_f32_e32 v186, v50, v186
	v_lshlrev_b32_e32 v198, 16, v165
	v_mul_f32_e32 v187, v51, v187
	v_sub_f32_e32 v188, v194, v100
	v_and_b32_e32 v199, 0xffff0000, v165
	v_sub_f32_e32 v189, v194, v101
	v_sub_f32_e32 v190, v194, v102
	v_mul_f32_e32 v196, v196, v118
	v_sub_f32_e32 v191, v194, v103
	v_exp_f32_e32 v188, v188
	v_mul_f32_e32 v197, v197, v118
	v_exp_f32_e32 v189, v189
	v_exp_f32_e32 v190, v190
	v_mul_f32_e32 v198, v198, v118
	v_exp_f32_e32 v191, v191
	v_mul_f32_e32 v188, v52, v188
	v_mul_f32_e32 v199, v199, v118
	v_mul_f32_e32 v189, v53, v189
	v_mul_f32_e32 v190, v54, v190
	v_cvt_pk_bf16_f32 v202, v196, v197
	v_mul_f32_e32 v191, v55, v191
	v_cvt_pk_bf16_f32 v128, v184, v185
	v_cvt_pk_bf16_f32 v203, v198, v199
	v_cvt_pk_bf16_f32 v129, v186, v187
	ds_write_b64 v215, v[202:203] offset:32768
	v_cvt_pk_bf16_f32 v130, v188, v189
	v_cvt_pk_bf16_f32 v131, v190, v191
	v_mul_f32_e32 v196, v196, v200
	s_waitcnt lgkmcnt(11)
	v_mfma_f32_16x16x32_bf16 v[24:27], v[56:59], v[128:131], v[24:27]
	ds_read_b128 v[96:99], v232 offset:128
	v_mul_f32_e32 v197, v197, v200
	s_waitcnt lgkmcnt(11)
	v_mfma_f32_16x16x32_bf16 v[48:51], v[64:67], v[28:31], 0
	s_waitcnt lgkmcnt(10)
	v_mfma_f32_16x16x32_bf16 v[48:51], v[68:71], v[32:35], v[48:51]
	v_mul_f32_e32 v198, v198, v200
	s_waitcnt lgkmcnt(9)
	v_mfma_f32_16x16x32_bf16 v[48:51], v[72:75], v[40:43], v[48:51]
	s_waitcnt lgkmcnt(8)
	v_mfma_f32_16x16x32_bf16 v[48:51], v[76:79], v[44:47], v[48:51]
	v_mul_f32_e32 v199, v199, v200
	s_waitcnt lgkmcnt(0)
	v_sub_f32_e32 v184, v194, v96
	v_sub_f32_e32 v185, v194, v97
	v_cvt_pk_bf16_f32 v192, v196, v197
	v_sub_f32_e32 v186, v194, v98
	v_sub_f32_e32 v187, v194, v99
	v_cvt_pk_bf16_f32 v193, v198, v199
	v_exp_f32_e32 v184, v184
	ds_write_b64 v215, v[192:193] offset:37888
	v_exp_f32_e32 v185, v185
	v_exp_f32_e32 v186, v186
	ds_write_b64 v217, v[164:165] offset:43008
	v_exp_f32_e32 v187, v187
	v_mul_f32_e32 v184, v48, v184
	ds_write_b64 v217, v[166:167] offset:47616
	v_mul_f32_e32 v185, v49, v185
	v_mul_f32_e32 v186, v50, v186
	v_mul_f32_e32 v201, 0x3fb8aa3b, v168
	v_mul_f32_e32 v187, v51, v187
	v_cndmask_b32_e64 v184, 0, v184, s[14:15]
	ds_write_b32 v218, v201 offset:256
	v_cndmask_b32_e64 v185, 0, v185, s[16:17]
	v_cndmask_b32_e64 v186, 0, v186, s[22:23]
	v_mul_f32_e32 v174, 0x3fb8aa3b, v169
	v_cndmask_b32_e64 v187, 0, v187, s[34:35]
	v_cvt_pk_bf16_f32 v128, v184, v185
	v_exp_f32_e32 v174, v174
	v_cvt_pk_bf16_f32 v129, v186, v187
	v_mov_b32_e32 v130, 0
	v_mov_b32_e32 v131, 0
	s_nop 1
	v_mfma_f32_16x16x32_bf16 v[24:27], v[60:63], v[128:131], v[24:27]
	s_mul_i32 s65, s56, 0x2000
	s_add_u32 s65, s65, 0x304f1000
	s_add_u32 s48, s0, s65
	s_addc_u32 s49, s1, 0
	s_nop 3
	v_fma_f32 v184, s61, v120, v24
	v_fma_f32 v185, s61, v121, v25
	v_fma_f32 v186, s61, v122, v26
	v_fma_f32 v187, s61, v123, v27
	v_mul_f32_e32 v184, v184, v112
	v_mul_f32_e32 v185, v185, v113
	v_mul_f32_e32 v186, v186, v114
	v_mul_f32_e32 v187, v187, v115
	v_cvt_pk_bf16_f32 v170, v184, v185
	v_cvt_pk_bf16_f32 v171, v186, v187
	global_store_dwordx2 v210, v[170:171], s[48:49]
	s_add_u32 s65, s54, 1
	s_sub_u32 s65, s65, s60
	s_lshl_b32 s65, s65, 6
	s_add_u32 s56, s65, s20
	s_waitcnt lgkmcnt(0)
	s_barrier
	s_add_u32 s54, s54, 1
	s_cmp_ge_u32 s54, s39
	s_cbranch_scc1 .Lssd_done
	ds_read_b128 v[28:31], v223 offset:8192
	ds_read_b128 v[32:35], v224 offset:8192
	ds_read_b128 v[40:43], v225 offset:8192
	ds_read_b128 v[44:47], v226 offset:8192
	ds_read_b128 v[48:51], v227 offset:8192
	ds_read_b128 v[52:55], v228 offset:8192
	ds_read_b128 v[56:59], v229 offset:8192
	ds_read_b128 v[60:63], v230 offset:8192
	ds_read_b32 v194, v231 offset:384
	ds_read_b128 v[64:67], v223 offset:16384
	ds_read_b128 v[68:71], v224 offset:16384
	ds_read_b128 v[72:75], v225 offset:16384
	ds_read_b128 v[76:79], v226 offset:16384
	ds_read_b128 v[80:83], v223 offset:20480
	ds_read_b128 v[84:87], v224 offset:20480
	global_load_dwordx4 v[156:159], v204, s[40:41] offset:2048
	s_waitcnt lgkmcnt(11)
	ds_read_b128 v[88:91], v225 offset:20480
	ds_read_b128 v[92:95], v226 offset:20480
	ds_read_b128 v[96:99], v232 offset:256
	ds_read_b128 v[100:103], v232 offset:320
	s_waitcnt lgkmcnt(11)
	ds_read_b64 v[124:125], v236 offset:45312
	global_load_dwordx4 v[160:163], v205, s[40:41] offset:2048
	ds_read_b64 v[126:127], v236 offset:49920
	v_mfma_f32_16x16x32_bf16 v[24:27], v[48:51], v[28:31], 0
	v_mfma_f32_16x16x32_bf16 v[24:27], v[52:55], v[32:35], v[24:27]
	v_mfma_f32_16x16x32_bf16 v[24:27], v[56:59], v[40:43], v[24:27]
	v_mfma_f32_16x16x32_bf16 v[24:27], v[60:63], v[44:47], v[24:27]
	ds_read_b64_tr_b16 v[56:57], v234 offset:32768
	global_load_dwordx4 v[148:151], v204, s[40:41]
	ds_read_b64_tr_b16 v[58:59], v234 offset:34048
	s_waitcnt lgkmcnt(13)
	v_mfma_f32_16x16x32_bf16 v[48:51], v[64:67], v[28:31], 0
	s_waitcnt lgkmcnt(9)
; __device__ __forceinline__ void phase_ssd(const Params& P, int seg, unsigned char* smem) {
;     ...
;             bf16x8 cf[4];
; #pragma unroll
;             for (int k = 0; k < 4; ++k) cf[k] = *(const bf16x8*)(sb + T_CS + (lt * 16 + fr) * 272 + (k * 32 + fq * 8) * 2);
;             f32x4 yo = {0.f, 0.f, 0.f, 0.f};
; #pragma unroll
;             for (int k = 0; k < 4; ++k) { const bf16x8 bb = *(const bf16x8*)((const unsigned char*)StR + (pt * 16 + fr) * 272 + (k * 32 + fq * 8) * 2); yo = mfma16(cf[k], bb, yo); }
; { const f32x4 a4 = *(const f32x4*)(acP + lt * 16 + fq * 4);
; #pragma unroll
;               for (int j = 0; j < 4; ++j) yo[j] *= __expf(a4[j]); }
;             const float acl_fr = acP[lt * 16 + fr]; const int lrow = lt * 16 + fr;
; #pragma unroll
;             for (int t = 0; t < 2; ++t) {
;                 if (2 * t <= lt) {
;                     v2u xb0, xb1;
;                     { const unsigned a0 = lds0 + par * T_BUF + T_XD + (32 * t + 4 * fq + tq) * 80 + (pt * 16 + 4 * tp) * 2, a1 = a0 + 16 * 80; TR_ISSUE(xb0, a0); TR_ISSUE(xb1, a1); }
;                     float m[8];
;                     { f32x4 s0 = {0.f, 0.f, 0.f, 0.f}, s1 = {0.f, 0.f, 0.f, 0.f};
; #pragma unroll
;                       for (int k = 0; k < 4; ++k) { const bf16x8 bf0 = *(const bf16x8*)(sb + T_BS + ((2 * t) * 16 + fr) * 272 + (k * 32 + fq * 8) * 2), bf1 = *(const bf16x8*)(sb + T_BS + ((2 * t + 1) * 16 + fr) * 272 + (k * 32 + fq * 8) * 2);
;                           s0 = mfma16(bf0, cf[k], s0); s1 = mfma16(bf1, cf[k], s1); }
;                       const f32x4 a0 = *(const f32x4*)(acP + (2 * t) * 16 + fq * 4), a1 = *(const f32x4*)(acP + (2 * t + 1) * 16 + fq * 4);
; #pragma unroll
;                       for (int j = 0; j < 4; ++j) { const int si0 = (2 * t) * 16 + fq * 4 + j, si1 = si0 + 16;
;                           const float e0 = s0[j] * __expf(fminf(acl_fr - a0[j], 0.f)), e1 = s1[j] * __expf(fminf(acl_fr - a1[j], 0.f));
;                           m[j] = (si0 <= lrow) ? e0 : 0.f; m[4 + j] = (si1 <= lrow) ? e1 : 0.f; } }
;                     v4u mp; mp.x = cvt_pk_bf16(m[0], m[1]); mp.y = cvt_pk_bf16(m[2], m[3]); mp.z = cvt_pk_bf16(m[4], m[5]); mp.w = cvt_pk_bf16(m[6], m[7]);
;                     asm volatile("s_waitcnt lgkmcnt(0)" : "+v"(xb0), "+v"(xb1) :: "memory");
;                     yo = mfma16(__builtin_bit_cast(bf16x8, mp), mk8(xb0, xb1), yo);
	v_mfma_f32_16x16x32_bf16 v[52:55], v[80:83], v[28:31], 0
	v_mfma_f32_16x16x32_bf16 v[48:51], v[68:71], v[32:35], v[48:51]
	s_waitcnt lgkmcnt(8)
	v_mfma_f32_16x16x32_bf16 v[52:55], v[84:87], v[32:35], v[52:55]
	global_load_dwordx4 v[152:155], v205, s[40:41]
	v_mfma_f32_16x16x32_bf16 v[48:51], v[72:75], v[40:43], v[48:51]
	s_waitcnt lgkmcnt(7)
	v_mfma_f32_16x16x32_bf16 v[52:55], v[88:91], v[40:43], v[52:55]
	v_mfma_f32_16x16x32_bf16 v[48:51], v[76:79], v[44:47], v[48:51]
	s_waitcnt lgkmcnt(6)
	v_mfma_f32_16x16x32_bf16 v[52:55], v[92:95], v[44:47], v[52:55]
	ds_read_b128 v[64:67], v223 offset:24576
	ds_read_b128 v[68:71], v224 offset:24576
	global_load_dwordx2 v[164:165], v206, s[40:41]
	ds_read_b128 v[72:75], v225 offset:24576
	ds_read_b128 v[76:79], v226 offset:24576
	ds_read_b64_tr_b16 v[60:61], v234 offset:35328
	ds_read_b64_tr_b16 v[62:63], v234 offset:36608
	v_exp_f32_e32 v195, v194
	s_nop 0
	v_mul_f32_e32 v24, v24, v195
	global_load_dwordx2 v[166:167], v207, s[42:43] nt
	v_mul_f32_e32 v25, v25, v195
	v_mul_f32_e32 v26, v26, v195
	v_mul_f32_e32 v27, v27, v195
	s_waitcnt lgkmcnt(8)
	v_lshlrev_b32_e32 v112, 16, v126
	v_and_b32_e32 v113, 0xffff0000, v126
	global_load_dword v118, v208, s[44:45]
	v_lshlrev_b32_e32 v114, 16, v127
	v_and_b32_e32 v115, 0xffff0000, v127
	v_mul_f32_e32 v120, 0xbfb8aa3b, v112
	v_mul_f32_e32 v121, 0xbfb8aa3b, v113
	v_mul_f32_e32 v122, 0xbfb8aa3b, v114
	v_mul_f32_e32 v123, 0xbfb8aa3b, v115
	global_load_dword v168, v208, s[46:47]
	v_exp_f32_e32 v120, v120
	v_exp_f32_e32 v121, v121
	v_exp_f32_e32 v122, v122
	v_exp_f32_e32 v123, v123
	v_add_f32_e32 v120, 1.0, v120
	global_load_dword v169, v209, s[46:47]
	v_add_f32_e32 v121, 1.0, v121
	v_add_f32_e32 v122, 1.0, v122
	v_add_f32_e32 v123, 1.0, v123
	v_rcp_f32_e32 v120, v120
	v_rcp_f32_e32 v121, v121
	v_rcp_f32_e32 v122, v122
	s_add_u32 s66, s54, 3
	s_cmp_lt_u32 s66, s39
	s_cselect_b32 s74, 0xc0000, 0
	s_cselect_b32 s75, 0x280000, 0
	s_cselect_b32 s76, 0x4000, 0
	s_add_u32 s40, s40, s74
	s_addc_u32 s41, s41, 0
	s_add_u32 s42, s42, s75
	s_addc_u32 s43, s43, 0
	s_add_u32 s44, s44, s76
	s_addc_u32 s45, s45, 0
	s_add_u32 s46, s46, s76
	s_addc_u32 s47, s47, 0
	v_rcp_f32_e32 v123, v123
	v_mul_f32_e32 v112, v120, v112
	s_waitcnt vmcnt(10)
	v_mul_f32_e32 v113, v121, v113
	v_mul_f32_e32 v114, v122, v114
	ds_write_b128 v212, v[140:143]
	v_mul_f32_e32 v115, v123, v115
	v_lshlrev_b32_e32 v120, 16, v124
	ds_write_b128 v212, v[144:147] offset:8192
	v_and_b32_e32 v121, 0xffff0000, v124
	ds_write_b128 v212, v[132:135] offset:16384
	v_lshlrev_b32_e32 v122, 16, v125
	v_and_b32_e32 v123, 0xffff0000, v125
	ds_write_b128 v212, v[136:139] offset:24576
	v_sub_f32_e32 v184, v194, v96
	v_sub_f32_e32 v185, v194, v97
	v_sub_f32_e32 v200, v117, v116
	v_sub_f32_e32 v186, v194, v98
	v_sub_f32_e32 v187, v194, v99
	v_mul_f32_e32 v200, 0x3fb8aa3b, v200
	v_exp_f32_e32 v184, v184
	v_exp_f32_e32 v185, v185
	v_exp_f32_e32 v200, v200
	v_exp_f32_e32 v186, v186
	v_exp_f32_e32 v187, v187
	v_lshlrev_b32_e32 v196, 16, v4
	v_mul_f32_e32 v184, v48, v184
	v_mul_f32_e32 v185, v49, v185
	v_and_b32_e32 v197, 0xffff0000, v4
	v_mul_f32_e32 v186, v50, v186
	v_lshlrev_b32_e32 v198, 16, v5
	v_mul_f32_e32 v187, v51, v187
	v_sub_f32_e32 v188, v194, v100
	v_and_b32_e32 v199, 0xffff0000, v5
	v_sub_f32_e32 v189, v194, v101
	v_sub_f32_e32 v190, v194, v102
	v_mul_f32_e32 v196, v196, v6
	v_sub_f32_e32 v191, v194, v103
	v_exp_f32_e32 v188, v188
	v_mul_f32_e32 v197, v197, v6
	v_exp_f32_e32 v189, v189
	v_exp_f32_e32 v190, v190
	v_mul_f32_e32 v198, v198, v6
	v_exp_f32_e32 v191, v191
	v_mul_f32_e32 v188, v52, v188
	v_mul_f32_e32 v199, v199, v6
	v_mul_f32_e32 v189, v53, v189
	v_mul_f32_e32 v190, v54, v190
	v_cvt_pk_bf16_f32 v202, v196, v197
	v_mul_f32_e32 v191, v55, v191
	v_cvt_pk_bf16_f32 v128, v184, v185
	v_cvt_pk_bf16_f32 v203, v198, v199
	v_cvt_pk_bf16_f32 v129, v186, v187
	ds_write_b64 v214, v[202:203] offset:32768
	v_cvt_pk_bf16_f32 v130, v188, v189
	v_cvt_pk_bf16_f32 v131, v190, v191
	v_mul_f32_e32 v196, v196, v200
	s_waitcnt lgkmcnt(11)
	v_mfma_f32_16x16x32_bf16 v[24:27], v[56:59], v[128:131], v[24:27]
	ds_read_b128 v[96:99], v232 offset:384
	v_mul_f32_e32 v197, v197, v200
	s_waitcnt lgkmcnt(11)
	v_mfma_f32_16x16x32_bf16 v[48:51], v[64:67], v[28:31], 0
	s_waitcnt lgkmcnt(10)
	v_mfma_f32_16x16x32_bf16 v[48:51], v[68:71], v[32:35], v[48:51]
	v_mul_f32_e32 v198, v198, v200
	s_waitcnt lgkmcnt(9)
	v_mfma_f32_16x16x32_bf16 v[48:51], v[72:75], v[40:43], v[48:51]
	s_waitcnt lgkmcnt(8)
	v_mfma_f32_16x16x32_bf16 v[48:51], v[76:79], v[44:47], v[48:51]
	v_mul_f32_e32 v199, v199, v200
	s_waitcnt lgkmcnt(0)
	v_sub_f32_e32 v184, v194, v96
	v_sub_f32_e32 v185, v194, v97
	v_cvt_pk_bf16_f32 v192, v196, v197
	v_sub_f32_e32 v186, v194, v98
	v_sub_f32_e32 v187, v194, v99
	v_cvt_pk_bf16_f32 v193, v198, v199
	v_exp_f32_e32 v184, v184
	ds_write_b64 v214, v[192:193] offset:37888
	v_exp_f32_e32 v185, v185
	v_exp_f32_e32 v186, v186
	ds_write_b64 v216, v[4:5] offset:43008
	v_exp_f32_e32 v187, v187
	v_mul_f32_e32 v184, v48, v184
	ds_write_b64 v216, v[36:37] offset:47616
	v_mul_f32_e32 v185, v49, v185
	v_mul_f32_e32 v186, v50, v186
	v_mul_f32_e32 v201, 0x3fb8aa3b, v116
	v_mul_f32_e32 v187, v51, v187
	v_cndmask_b32_e64 v184, 0, v184, s[14:15]
	ds_write_b32 v218, v201
	v_cndmask_b32_e64 v185, 0, v185, s[16:17]
	v_cndmask_b32_e64 v186, 0, v186, s[22:23]
	v_mul_f32_e32 v174, 0x3fb8aa3b, v117
	v_cndmask_b32_e64 v187, 0, v187, s[34:35]
	v_cvt_pk_bf16_f32 v128, v184, v185
	v_exp_f32_e32 v174, v174
	v_cvt_pk_bf16_f32 v129, v186, v187
	v_mov_b32_e32 v130, 0
	v_mov_b32_e32 v131, 0
	s_nop 1
	v_mfma_f32_16x16x32_bf16 v[24:27], v[60:63], v[128:131], v[24:27]
	s_mul_i32 s65, s56, 0x2000
	s_add_u32 s65, s65, 0x304f1000
	s_add_u32 s48, s0, s65
	s_addc_u32 s49, s1, 0
	s_nop 3
	v_fma_f32 v184, s61, v120, v24
	v_fma_f32 v185, s61, v121, v25
	v_fma_f32 v186, s61, v122, v26
	v_fma_f32 v187, s61, v123, v27
	v_mul_f32_e32 v184, v184, v112
	v_mul_f32_e32 v185, v185, v113
	v_mul_f32_e32 v186, v186, v114
	v_mul_f32_e32 v187, v187, v115
	v_cvt_pk_bf16_f32 v170, v184, v185
	v_cvt_pk_bf16_f32 v171, v186, v187
	global_store_dwordx2 v210, v[170:171], s[48:49]
	s_add_u32 s65, s54, 1
	s_sub_u32 s65, s65, s60
	s_lshl_b32 s65, s65, 6
	s_add_u32 s56, s65, s20
	s_waitcnt lgkmcnt(0)
	s_barrier
	s_add_u32 s54, s54, 1
	s_cmp_lt_u32 s54, s39
	s_cbranch_scc1 .Lssd_loop2
	s_branch .Lssd_done
	.p2align	6
